# in-structure slot trimming of the GEMM mainloops: M0 wait-state nops replaced by pending LDS reads + redundant post-barrier waits removed
# speedup vs baseline: 1.0026x; 1.0026x over previous
; #define PG8_STAGE(bufoff, gbase, voff) do { _Pragma("unroll") for (int _i = 0; _i < 2; ++_i) \
;         __builtin_amdgcn_global_load_lds((const unsigned*)((const char*)(gbase) + (voff)[_i]), (PG8_LAS unsigned*)(lds + (bufoff) + ldsw + _i * 8192), 16, 0, 0); } while (0)
; #define PG8_LDA(dst, b, h) do { _Pragma("unroll") for (int m = 0; m < 4; ++m) _Pragma("unroll") for (int k = 0; k < 2; ++k) dst[m][k] = *(const PG8_LAS bf16x8*)(lds + PG8_SA(b, h) + aoff + m * 2048 + k * 1024); } while (0)
; #define PG8_LDB(dst, b, h) do { _Pragma("unroll") for (int n = 0; n < 2; ++n) _Pragma("unroll") for (int k = 0; k < 2; ++k) dst[n][k] = *(const PG8_LAS bf16x8*)(lds + PG8_SB(b, h) + boff + n * 2048 + k * 1024); } while (0)
; #define PG8_MMA(ai, bj, At, Bt) do { __builtin_amdgcn_s_setprio(1); _Pragma("unroll") for (int m = 0; m < 4; ++m) _Pragma("unroll") for (int n = 0; n < 2; ++n) _Pragma("unroll") for (int k = 0; k < 2; ++k) \
;         acc[ai][bj][m][n] = __builtin_amdgcn_mfma_f32_16x16x32_bf16(Bt[n][k], At[m][k], acc[ai][bj][m][n], 0, 0, 0); __builtin_amdgcn_s_setprio(0); } while (0)
; #define PG8_WAIT_V(n) asm volatile("s_waitcnt vmcnt(" #n ")" ::: "memory")
; #define PG8_WAIT_L(n) asm volatile("s_waitcnt lgkmcnt(" #n ")" ::: "memory")
; template <class Epi, class Sched, bool ALIGN_EPI = false, bool SP2 = false>
; __device__ __forceinline__ void gemm_phase(PG8_LAS unsigned char* lds, const Gemm g, const Sched& S, const Epi& E, int tid_in) {
;     ...
;             const bool last = (t == nt - 2);
;             const char* a1 = cA + (size_t)(t + 1) * kstep;
;             const char* a2 = last ? nA : cA + (size_t)(t + 2) * kstep; const char* b2 = last ? nB : cB + (size_t)(t + 2) * kstep;
;             const char* a3 = a2 + kstep; const char* b3 = b2 + kstep;
;             if (last && has_next) S.a_ready(nxt);
;             if constexpr (SP2) {
;             PG8_LDB(B0, 0, 0); PG8_LDB(B1, 0, 1); PG8_SCHED; PG8_LDA(At, 0, 0); PG8_STAGE(PG8_SA(1, 1), a1 + hstepA, voffA);
;             PG8_WAIT_V(8); PG8_WAIT_L(0); PG8_BAR; PG8_MMA(0, 0, At, B0); PG8_MMA(0, 1, At, B1); PG8_BAR; PG8_SCHED;
;             PG8_LDA(At, 0, 1); PG8_STAGE(PG8_SB(0, 0), b2, voffB); PG8_STAGE(PG8_SB(0, 1), b2 + hstep, voffB); PG8_STAGE(PG8_SA(0, 0), a2, voffA);
;             PG8_WAIT_V(8); PG8_WAIT_L(0); PG8_BAR; PG8_MMA(1, 0, At, B0); PG8_MMA(1, 1, At, B1); PG8_BAR; PG8_SCHED;
.LBB0_204:
	s_add_u32 s10, s2, 0xfffc0080
	s_addc_u32 s11, s3, -1
	s_add_i32 s28, 0, 0x10000
	s_cmp_eq_u32 s27, 12
	s_cselect_b32 s13, s15, s11
	s_cselect_b32 s12, s20, s10
	v_add_u32_e32 v156, s28, v159
	s_cselect_b32 s11, s21, s26
	s_cselect_b32 s10, s24, s25
	s_add_i32 s52, 0, 0x14000
	ds_read_b128 v[144:147], v156
	ds_read_b128 v[148:151], v156 offset:1024
	ds_read_b128 v[152:155], v156 offset:2048
	ds_read_b128 v[162:165], v156 offset:3072
	v_add_u32_e32 v156, s52, v159
	ds_read_b128 v[166:169], v156
	ds_read_b128 v[170:173], v156 offset:1024
	ds_read_b128 v[174:177], v156 offset:2048
	ds_read_b128 v[178:181], v156 offset:3072
	s_add_i32 m0, s35, 0xc000
	ds_read_b128 v[182:185], v160
	ds_read_b128 v[186:189], v160 offset:1024
	ds_read_b128 v[200:203], v160 offset:2048
	ds_read_b128 v[204:207], v160 offset:3072
	ds_read_b128 v[208:211], v160 offset:4096
	ds_read_b128 v[212:215], v160 offset:5120
	ds_read_b128 v[216:219], v160 offset:6144
	global_load_lds_dwordx4 v142, s[2:3]
	s_add_i32 m0, s35, 0xe000
	ds_read_b128 v[226:229], v160 offset:7168
	global_load_lds_dwordx4 v140, s[2:3]
	s_waitcnt vmcnt(8)
	s_waitcnt lgkmcnt(0)
	s_barrier
	s_setprio 1
	v_mfma_f32_16x16x32_bf16 v[124:127], v[144:147], v[182:185], v[124:127]
	v_mfma_f32_16x16x32_bf16 v[120:123], v[152:155], v[182:185], v[120:123]
	v_mfma_f32_16x16x32_bf16 v[108:111], v[144:147], v[200:203], v[108:111]
	v_mfma_f32_16x16x32_bf16 v[104:107], v[152:155], v[200:203], v[104:107]
	v_mfma_f32_16x16x32_bf16 v[92:95], v[144:147], v[208:211], v[92:95]
	v_mfma_f32_16x16x32_bf16 v[88:91], v[152:155], v[208:211], v[88:91]
	v_mfma_f32_16x16x32_bf16 v[76:79], v[144:147], v[216:219], v[76:79]
	v_mfma_f32_16x16x32_bf16 v[72:75], v[152:155], v[216:219], v[72:75]
	v_mfma_f32_16x16x32_bf16 v[124:127], v[148:151], v[186:189], v[124:127]
	v_mfma_f32_16x16x32_bf16 v[120:123], v[162:165], v[186:189], v[120:123]
	v_mfma_f32_16x16x32_bf16 v[108:111], v[148:151], v[204:207], v[108:111]
	v_mfma_f32_16x16x32_bf16 v[104:107], v[162:165], v[204:207], v[104:107]
	v_mfma_f32_16x16x32_bf16 v[92:95], v[148:151], v[212:215], v[92:95]
	v_mfma_f32_16x16x32_bf16 v[88:91], v[162:165], v[212:215], v[88:91]
	v_mfma_f32_16x16x32_bf16 v[76:79], v[148:151], v[226:229], v[76:79]
	v_mfma_f32_16x16x32_bf16 v[72:75], v[162:165], v[226:229], v[72:75]
	s_setprio 0
	s_setprio 1
	v_mfma_f32_16x16x32_bf16 v[116:119], v[166:169], v[182:185], v[116:119]
	v_mfma_f32_16x16x32_bf16 v[112:115], v[174:177], v[182:185], v[112:115]
	v_mfma_f32_16x16x32_bf16 v[100:103], v[166:169], v[200:203], v[100:103]
	v_mfma_f32_16x16x32_bf16 v[96:99], v[174:177], v[200:203], v[96:99]
	v_mfma_f32_16x16x32_bf16 v[84:87], v[166:169], v[208:211], v[84:87]
	v_mfma_f32_16x16x32_bf16 v[80:83], v[174:177], v[208:211], v[80:83]
	v_mfma_f32_16x16x32_bf16 v[68:71], v[166:169], v[216:219], v[68:71]
	v_mfma_f32_16x16x32_bf16 v[64:67], v[174:177], v[216:219], v[64:67]
	v_mfma_f32_16x16x32_bf16 v[116:119], v[170:173], v[186:189], v[116:119]
	v_mfma_f32_16x16x32_bf16 v[112:115], v[178:181], v[186:189], v[112:115]
	v_mfma_f32_16x16x32_bf16 v[100:103], v[170:173], v[204:207], v[100:103]
	v_mfma_f32_16x16x32_bf16 v[96:99], v[178:181], v[204:207], v[96:99]
	v_mfma_f32_16x16x32_bf16 v[84:87], v[170:173], v[212:215], v[84:87]
	v_mfma_f32_16x16x32_bf16 v[80:83], v[178:181], v[212:215], v[80:83]
	v_mfma_f32_16x16x32_bf16 v[68:71], v[170:173], v[226:229], v[68:71]
	v_mfma_f32_16x16x32_bf16 v[64:67], v[178:181], v[226:229], v[64:67]
	s_setprio 0
	s_barrier
	s_add_i32 s28, s28, s34
	s_mov_b32 m0, s28
	ds_read_b128 v[182:185], v160 offset:16384
	ds_read_b128 v[186:189], v160 offset:17408
	ds_read_b128 v[200:203], v160 offset:18432
	ds_read_b128 v[204:207], v160 offset:19456
	ds_read_b128 v[208:211], v160 offset:20480
	global_load_lds_dwordx4 v132, s[10:11]
	s_add_i32 m0, s28, 0x2000
	s_add_u32 s28, s10, 0x40000
	s_addc_u32 s29, s11, 0
	s_add_i32 s52, s52, s34
	global_load_lds_dwordx4 v128, s[10:11]
	s_mov_b32 m0, s52
	s_mov_b64 s[100:101], s[12:13]
	global_load_lds_dwordx4 v132, s[28:29]
	s_add_i32 m0, s52, 0x2000
	ds_read_b128 v[212:215], v160 offset:21504
	global_load_lds_dwordx4 v128, s[28:29]
	s_mov_b32 m0, s35
	ds_read_b128 v[216:219], v160 offset:22528
	global_load_lds_dwordx4 v134, s[100:101]
	s_mov_b32 m0, s38
	ds_read_b128 v[226:229], v160 offset:23552
	global_load_lds_dwordx4 v130, s[100:101]
	s_waitcnt vmcnt(8)
	s_waitcnt lgkmcnt(0)
	s_barrier
	s_setprio 1
	v_mfma_f32_16x16x32_bf16 v[60:63], v[144:147], v[182:185], v[60:63]
	v_mfma_f32_16x16x32_bf16 v[56:59], v[152:155], v[182:185], v[56:59]
	v_mfma_f32_16x16x32_bf16 v[44:47], v[144:147], v[200:203], v[44:47]
	v_mfma_f32_16x16x32_bf16 v[40:43], v[152:155], v[200:203], v[40:43]
	v_mfma_f32_16x16x32_bf16 v[28:31], v[144:147], v[208:211], v[28:31]
	v_mfma_f32_16x16x32_bf16 v[24:27], v[152:155], v[208:211], v[24:27]
	v_mfma_f32_16x16x32_bf16 v[12:15], v[144:147], v[216:219], v[12:15]
	v_mfma_f32_16x16x32_bf16 v[8:11], v[152:155], v[216:219], v[8:11]
	v_mfma_f32_16x16x32_bf16 v[60:63], v[148:151], v[186:189], v[60:63]
	v_mfma_f32_16x16x32_bf16 v[56:59], v[162:165], v[186:189], v[56:59]
	v_mfma_f32_16x16x32_bf16 v[44:47], v[148:151], v[204:207], v[44:47]
	v_mfma_f32_16x16x32_bf16 v[40:43], v[162:165], v[204:207], v[40:43]
	v_mfma_f32_16x16x32_bf16 v[28:31], v[148:151], v[212:215], v[28:31]
	v_mfma_f32_16x16x32_bf16 v[24:27], v[162:165], v[212:215], v[24:27]
	v_mfma_f32_16x16x32_bf16 v[12:15], v[148:151], v[226:229], v[12:15]
	v_mfma_f32_16x16x32_bf16 v[8:11], v[162:165], v[226:229], v[8:11]
	s_setprio 0
	s_setprio 1
	v_mfma_f32_16x16x32_bf16 v[52:55], v[166:169], v[182:185], v[52:55]
	v_mfma_f32_16x16x32_bf16 v[48:51], v[174:177], v[182:185], v[48:51]
	v_mfma_f32_16x16x32_bf16 v[36:39], v[166:169], v[200:203], v[36:39]
	v_mfma_f32_16x16x32_bf16 v[32:35], v[174:177], v[200:203], v[32:35]
	v_mfma_f32_16x16x32_bf16 v[20:23], v[166:169], v[208:211], v[20:23]
	v_mfma_f32_16x16x32_bf16 v[16:19], v[174:177], v[208:211], v[16:19]
	v_mfma_f32_16x16x32_bf16 v[4:7], v[166:169], v[216:219], v[4:7]
	v_mfma_f32_16x16x32_bf16 v[0:3], v[174:177], v[216:219], v[0:3]
	v_mfma_f32_16x16x32_bf16 v[52:55], v[170:173], v[186:189], v[52:55]
	v_mfma_f32_16x16x32_bf16 v[48:51], v[178:181], v[186:189], v[48:51]
	v_mfma_f32_16x16x32_bf16 v[36:39], v[170:173], v[204:207], v[36:39]
	v_mfma_f32_16x16x32_bf16 v[32:35], v[178:181], v[204:207], v[32:35]
	v_mfma_f32_16x16x32_bf16 v[20:23], v[170:173], v[212:215], v[20:23]
	v_mfma_f32_16x16x32_bf16 v[16:19], v[178:181], v[212:215], v[16:19]
	v_mfma_f32_16x16x32_bf16 v[4:7], v[170:173], v[226:229], v[4:7]
	v_mfma_f32_16x16x32_bf16 v[0:3], v[178:181], v[226:229], v[0:3]
	s_setprio 0
	s_barrier
; #define PG8_STAGE(bufoff, gbase, voff) do { _Pragma("unroll") for (int _i = 0; _i < 2; ++_i) \
;         __builtin_amdgcn_global_load_lds((const unsigned*)((const char*)(gbase) + (voff)[_i]), (PG8_LAS unsigned*)(lds + (bufoff) + ldsw + _i * 8192), 16, 0, 0); } while (0)
; #define PG8_LDA(dst, b, h) do { _Pragma("unroll") for (int m = 0; m < 4; ++m) _Pragma("unroll") for (int k = 0; k < 2; ++k) dst[m][k] = *(const PG8_LAS bf16x8*)(lds + PG8_SA(b, h) + aoff + m * 2048 + k * 1024); } while (0)
; #define PG8_LDB(dst, b, h) do { _Pragma("unroll") for (int n = 0; n < 2; ++n) _Pragma("unroll") for (int k = 0; k < 2; ++k) dst[n][k] = *(const PG8_LAS bf16x8*)(lds + PG8_SB(b, h) + boff + n * 2048 + k * 1024); } while (0)
; #define PG8_MMA(ai, bj, At, Bt) do { __builtin_amdgcn_s_setprio(1); _Pragma("unroll") for (int m = 0; m < 4; ++m) _Pragma("unroll") for (int n = 0; n < 2; ++n) _Pragma("unroll") for (int k = 0; k < 2; ++k) \
;         acc[ai][bj][m][n] = __builtin_amdgcn_mfma_f32_16x16x32_bf16(Bt[n][k], At[m][k], acc[ai][bj][m][n], 0, 0, 0); __builtin_amdgcn_s_setprio(0); } while (0)
; #define PG8_WAIT_V(n) asm volatile("s_waitcnt vmcnt(" #n ")" ::: "memory")
; #define PG8_WAIT_L(n) asm volatile("s_waitcnt lgkmcnt(" #n ")" ::: "memory")
; #define PG8_BAR __builtin_amdgcn_s_barrier()
; #define PG8_SCHED __builtin_amdgcn_sched_barrier(0)
; template <class Epi, class Sched, bool ALIGN_EPI = false, bool SP2 = false>
; __device__ __forceinline__ void gemm_phase(PG8_LAS unsigned char* lds, const Gemm g, const Sched& S, const Epi& E, int tid_in) {
;     ...
;             PG8_LDB(B0, 1, 0); PG8_LDB(B1, 1, 1); PG8_SCHED; PG8_LDA(At, 1, 0); PG8_STAGE(PG8_SA(0, 1), a2 + hstepA, voffA);
;             PG8_WAIT_V(8); PG8_WAIT_L(0); PG8_BAR; PG8_MMA(0, 0, At, B0); PG8_MMA(0, 1, At, B1); PG8_BAR; PG8_SCHED;
;             PG8_LDA(At, 1, 1); PG8_STAGE(PG8_SB(1, 0), b3, voffB); PG8_STAGE(PG8_SB(1, 1), b3 + hstep, voffB); PG8_STAGE(PG8_SA(1, 0), a3, voffA);
;             PG8_WAIT_V(8); PG8_WAIT_L(0); PG8_BAR; PG8_MMA(1, 0, At, B0); PG8_MMA(1, 1, At, B1); PG8_BAR; PG8_SCHED;
	s_add_i32 s28, 0, 0x18000
	v_add_u32_e32 v161, s28, v159
	s_add_i32 s29, 0, 0x1c000
	ds_read_b128 v[144:147], v161
	ds_read_b128 v[148:151], v161 offset:1024
	ds_read_b128 v[152:155], v161 offset:2048
	ds_read_b128 v[162:165], v161 offset:3072
	v_add_u32_e32 v161, s29, v159
	ds_read_b128 v[166:169], v161
	ds_read_b128 v[170:173], v161 offset:1024
	ds_read_b128 v[174:177], v161 offset:2048
	ds_read_b128 v[178:181], v161 offset:3072
	s_add_u32 s12, s12, 0x40000
	s_addc_u32 s13, s13, 0
	s_mov_b32 m0, s77
	ds_read_b128 v[182:185], v160 offset:32768
	ds_read_b128 v[186:189], v160 offset:33792
	ds_read_b128 v[200:203], v160 offset:34816
	ds_read_b128 v[204:207], v160 offset:35840
	ds_read_b128 v[208:211], v160 offset:36864
	ds_read_b128 v[212:215], v160 offset:37888
	ds_read_b128 v[216:219], v160 offset:38912
	global_load_lds_dwordx4 v134, s[12:13]
	s_mov_b32 m0, s78
	ds_read_b128 v[226:229], v160 offset:39936
	global_load_lds_dwordx4 v130, s[12:13]
	s_waitcnt vmcnt(8)
	s_waitcnt lgkmcnt(0)
	s_barrier
	s_setprio 1
	v_mfma_f32_16x16x32_bf16 v[124:127], v[144:147], v[182:185], v[124:127]
	v_mfma_f32_16x16x32_bf16 v[120:123], v[152:155], v[182:185], v[120:123]
	v_mfma_f32_16x16x32_bf16 v[108:111], v[144:147], v[200:203], v[108:111]
	v_mfma_f32_16x16x32_bf16 v[104:107], v[152:155], v[200:203], v[104:107]
	v_mfma_f32_16x16x32_bf16 v[92:95], v[144:147], v[208:211], v[92:95]
	v_mfma_f32_16x16x32_bf16 v[88:91], v[152:155], v[208:211], v[88:91]
	v_mfma_f32_16x16x32_bf16 v[76:79], v[144:147], v[216:219], v[76:79]
	v_mfma_f32_16x16x32_bf16 v[72:75], v[152:155], v[216:219], v[72:75]
	v_mfma_f32_16x16x32_bf16 v[124:127], v[148:151], v[186:189], v[124:127]
	v_mfma_f32_16x16x32_bf16 v[120:123], v[162:165], v[186:189], v[120:123]
	v_mfma_f32_16x16x32_bf16 v[108:111], v[148:151], v[204:207], v[108:111]
	v_mfma_f32_16x16x32_bf16 v[104:107], v[162:165], v[204:207], v[104:107]
	v_mfma_f32_16x16x32_bf16 v[92:95], v[148:151], v[212:215], v[92:95]
	v_mfma_f32_16x16x32_bf16 v[88:91], v[162:165], v[212:215], v[88:91]
	v_mfma_f32_16x16x32_bf16 v[76:79], v[148:151], v[226:229], v[76:79]
	v_mfma_f32_16x16x32_bf16 v[72:75], v[162:165], v[226:229], v[72:75]
	s_setprio 0
	s_setprio 1
	v_mfma_f32_16x16x32_bf16 v[116:119], v[166:169], v[182:185], v[116:119]
	v_mfma_f32_16x16x32_bf16 v[112:115], v[174:177], v[182:185], v[112:115]
	v_mfma_f32_16x16x32_bf16 v[100:103], v[166:169], v[200:203], v[100:103]
	v_mfma_f32_16x16x32_bf16 v[96:99], v[174:177], v[200:203], v[96:99]
	v_mfma_f32_16x16x32_bf16 v[84:87], v[166:169], v[208:211], v[84:87]
	v_mfma_f32_16x16x32_bf16 v[80:83], v[174:177], v[208:211], v[80:83]
	v_mfma_f32_16x16x32_bf16 v[68:71], v[166:169], v[216:219], v[68:71]
	v_mfma_f32_16x16x32_bf16 v[64:67], v[174:177], v[216:219], v[64:67]
	v_mfma_f32_16x16x32_bf16 v[116:119], v[170:173], v[186:189], v[116:119]
	v_mfma_f32_16x16x32_bf16 v[112:115], v[178:181], v[186:189], v[112:115]
	v_mfma_f32_16x16x32_bf16 v[100:103], v[170:173], v[204:207], v[100:103]
	v_mfma_f32_16x16x32_bf16 v[96:99], v[178:181], v[204:207], v[96:99]
	v_mfma_f32_16x16x32_bf16 v[84:87], v[170:173], v[212:215], v[84:87]
	v_mfma_f32_16x16x32_bf16 v[80:83], v[178:181], v[212:215], v[80:83]
	v_mfma_f32_16x16x32_bf16 v[68:71], v[170:173], v[226:229], v[68:71]
	v_mfma_f32_16x16x32_bf16 v[64:67], v[178:181], v[226:229], v[64:67]
	s_setprio 0
	s_barrier
	s_add_i32 s12, s28, s34
	s_mov_b32 m0, s12
	ds_read_b128 v[182:185], v160 offset:49152
	ds_read_b128 v[186:189], v160 offset:50176
	ds_read_b128 v[200:203], v160 offset:51200
	ds_read_b128 v[204:207], v160 offset:52224
	s_add_u32 s10, s10, 0x80
	s_addc_u32 s11, s11, 0
	global_load_lds_dwordx4 v132, s[10:11]
	s_add_i32 m0, s12, 0x2000
	ds_read_b128 v[208:211], v160 offset:53248
	global_load_lds_dwordx4 v128, s[10:11]
	s_add_u32 s10, s10, 0x40000
	s_addc_u32 s11, s11, 0
	s_add_i32 s12, s29, s34
	s_mov_b32 m0, s12
	ds_read_b128 v[212:215], v160 offset:54272
	global_load_lds_dwordx4 v132, s[10:11]
	s_add_i32 m0, s12, 0x2000
	ds_read_b128 v[216:219], v160 offset:55296
	global_load_lds_dwordx4 v128, s[10:11]
	s_mov_b32 m0, s83
	s_nop 0
	s_add_u32 s100, s100, 0x80
	s_addc_u32 s101, s101, 0
	global_load_lds_dwordx4 v134, s[100:101]
	s_mov_b32 m0, s84
	ds_read_b128 v[226:229], v160 offset:56320
	global_load_lds_dwordx4 v130, s[100:101]
	s_waitcnt vmcnt(8)
	s_waitcnt lgkmcnt(0)
	s_barrier
	s_setprio 1
	v_mfma_f32_16x16x32_bf16 v[60:63], v[144:147], v[182:185], v[60:63]
	v_mfma_f32_16x16x32_bf16 v[56:59], v[152:155], v[182:185], v[56:59]
	v_mfma_f32_16x16x32_bf16 v[44:47], v[144:147], v[200:203], v[44:47]
	v_mfma_f32_16x16x32_bf16 v[40:43], v[152:155], v[200:203], v[40:43]
	v_mfma_f32_16x16x32_bf16 v[28:31], v[144:147], v[208:211], v[28:31]
	v_mfma_f32_16x16x32_bf16 v[24:27], v[152:155], v[208:211], v[24:27]
	v_mfma_f32_16x16x32_bf16 v[12:15], v[144:147], v[216:219], v[12:15]
	v_mfma_f32_16x16x32_bf16 v[8:11], v[152:155], v[216:219], v[8:11]
	v_mfma_f32_16x16x32_bf16 v[60:63], v[148:151], v[186:189], v[60:63]
	v_mfma_f32_16x16x32_bf16 v[56:59], v[162:165], v[186:189], v[56:59]
	v_mfma_f32_16x16x32_bf16 v[44:47], v[148:151], v[204:207], v[44:47]
	v_mfma_f32_16x16x32_bf16 v[40:43], v[162:165], v[204:207], v[40:43]
	v_mfma_f32_16x16x32_bf16 v[28:31], v[148:151], v[212:215], v[28:31]
	v_mfma_f32_16x16x32_bf16 v[24:27], v[162:165], v[212:215], v[24:27]
	v_mfma_f32_16x16x32_bf16 v[12:15], v[148:151], v[226:229], v[12:15]
	v_mfma_f32_16x16x32_bf16 v[8:11], v[162:165], v[226:229], v[8:11]
	s_setprio 0
	s_setprio 1
	v_mfma_f32_16x16x32_bf16 v[52:55], v[166:169], v[182:185], v[52:55]
	v_mfma_f32_16x16x32_bf16 v[48:51], v[174:177], v[182:185], v[48:51]
	v_mfma_f32_16x16x32_bf16 v[36:39], v[166:169], v[200:203], v[36:39]
	v_mfma_f32_16x16x32_bf16 v[32:35], v[174:177], v[200:203], v[32:35]
	v_mfma_f32_16x16x32_bf16 v[20:23], v[166:169], v[208:211], v[20:23]
	v_mfma_f32_16x16x32_bf16 v[16:19], v[174:177], v[208:211], v[16:19]
	v_mfma_f32_16x16x32_bf16 v[4:7], v[166:169], v[216:219], v[4:7]
	v_mfma_f32_16x16x32_bf16 v[0:3], v[174:177], v[216:219], v[0:3]
	v_mfma_f32_16x16x32_bf16 v[52:55], v[170:173], v[186:189], v[52:55]
	v_mfma_f32_16x16x32_bf16 v[48:51], v[178:181], v[186:189], v[48:51]
	v_mfma_f32_16x16x32_bf16 v[36:39], v[170:173], v[204:207], v[36:39]
	v_mfma_f32_16x16x32_bf16 v[32:35], v[178:181], v[204:207], v[32:35]
	v_mfma_f32_16x16x32_bf16 v[20:23], v[170:173], v[212:215], v[20:23]
	v_mfma_f32_16x16x32_bf16 v[16:19], v[178:181], v[212:215], v[16:19]
	v_mfma_f32_16x16x32_bf16 v[4:7], v[170:173], v[226:229], v[4:7]
	v_mfma_f32_16x16x32_bf16 v[0:3], v[178:181], v[226:229], v[0:3]
	s_setprio 0
	s_barrier
	s_add_i32 s27, s27, 2
	s_add_u32 s25, s25, 0x100
	s_addc_u32 s26, s26, 0
	s_add_u32 s2, s2, 0x100
	s_addc_u32 s3, s3, 0
	s_cmp_gt_u32 s27, 13
	s_cbranch_scc0 .LBB0_204
	s_and_b64 vcc, exec, s[62:63]
	s_cbranch_vccz .LBB0_207
	s_barrier

; #define PG8_STAGE(bufoff, gbase, voff) do { _Pragma("unroll") for (int _i = 0; _i < 2; ++_i) \
;         __builtin_amdgcn_global_load_lds((const unsigned*)((const char*)(gbase) + (voff)[_i]), (PG8_LAS unsigned*)(lds + (bufoff) + ldsw + _i * 8192), 16, 0, 0); } while (0)
; #define PG8_LDA(dst, b, h) do { _Pragma("unroll") for (int m = 0; m < 4; ++m) _Pragma("unroll") for (int k = 0; k < 2; ++k) dst[m][k] = *(const PG8_LAS bf16x8*)(lds + PG8_SA(b, h) + aoff + m * 2048 + k * 1024); } while (0)
; #define PG8_LDB(dst, b, h) do { _Pragma("unroll") for (int n = 0; n < 2; ++n) _Pragma("unroll") for (int k = 0; k < 2; ++k) dst[n][k] = *(const PG8_LAS bf16x8*)(lds + PG8_SB(b, h) + boff + n * 2048 + k * 1024); } while (0)
; #define PG8_MMA(ai, bj, At, Bt) do { __builtin_amdgcn_s_setprio(1); _Pragma("unroll") for (int m = 0; m < 4; ++m) _Pragma("unroll") for (int n = 0; n < 2; ++n) _Pragma("unroll") for (int k = 0; k < 2; ++k) \
;         acc[ai][bj][m][n] = __builtin_amdgcn_mfma_f32_16x16x32_bf16(Bt[n][k], At[m][k], acc[ai][bj][m][n], 0, 0, 0); __builtin_amdgcn_s_setprio(0); } while (0)
; #define PG8_WAIT_V(n) asm volatile("s_waitcnt vmcnt(" #n ")" ::: "memory")
; #define PG8_WAIT_L(n) asm volatile("s_waitcnt lgkmcnt(" #n ")" ::: "memory")
; template <class Epi, class Sched, bool ALIGN_EPI = false, bool SP2 = false>
; __device__ __forceinline__ void gemm_phase(PG8_LAS unsigned char* lds, const Gemm g, const Sched& S, const Epi& E, int tid_in) {
;     ...
;             const bool last = (t == nt - 2);
;             const char* a1 = cA + (size_t)(t + 1) * kstep;
;             const char* a2 = last ? nA : cA + (size_t)(t + 2) * kstep; const char* b2 = last ? nB : cB + (size_t)(t + 2) * kstep;
;             const char* a3 = a2 + kstep; const char* b3 = b2 + kstep;
;             if (last && has_next) S.a_ready(nxt);
;             if constexpr (SP2) {
;             PG8_LDB(B0, 0, 0); PG8_LDB(B1, 0, 1); PG8_SCHED; PG8_LDA(At, 0, 0); PG8_STAGE(PG8_SA(1, 1), a1 + hstepA, voffA);
;             PG8_WAIT_V(8); PG8_WAIT_L(0); PG8_BAR; PG8_MMA(0, 0, At, B0); PG8_MMA(0, 1, At, B1); PG8_BAR; PG8_SCHED;
;             PG8_LDA(At, 0, 1); PG8_STAGE(PG8_SB(0, 0), b2, voffB); PG8_STAGE(PG8_SB(0, 1), b2 + hstep, voffB); PG8_STAGE(PG8_SA(0, 0), a2, voffA);
;             PG8_WAIT_V(8); PG8_WAIT_L(0); PG8_BAR; PG8_MMA(1, 0, At, B0); PG8_MMA(1, 1, At, B1); PG8_BAR; PG8_SCHED;
.LBB0_526:
	s_add_u32 s12, s2, 0xfffc0080
	s_addc_u32 s13, s3, -1
	s_add_i32 s66, 0, 0x10000
	s_cmp_eq_u32 s65, 12
	s_cselect_b32 s15, s45, s13
	s_cselect_b32 s14, s46, s12
	v_add_u32_e32 v148, s66, v151
	s_cselect_b32 s13, s29, s64
	s_cselect_b32 s12, s47, s51
	s_add_i32 s68, 0, 0x14000
	ds_read_b128 v[140:143], v148
	ds_read_b128 v[144:147], v148 offset:1024
	ds_read_b128 v[160:163], v148 offset:2048
	ds_read_b128 v[164:167], v148 offset:3072
	v_add_u32_e32 v148, s68, v151
	ds_read_b128 v[168:171], v148
	ds_read_b128 v[172:175], v148 offset:1024
	ds_read_b128 v[176:179], v148 offset:2048
	ds_read_b128 v[180:183], v148 offset:3072
	s_add_i32 m0, s56, 0xc000
	ds_read_b128 v[184:187], v156
	ds_read_b128 v[200:203], v156 offset:1024
	ds_read_b128 v[204:207], v156 offset:2048
	ds_read_b128 v[208:211], v156 offset:3072
	ds_read_b128 v[212:215], v156 offset:4096
	ds_read_b128 v[216:219], v156 offset:5120
	ds_read_b128 v[226:229], v156 offset:6144
	global_load_lds_dwordx4 v138, s[2:3]
	s_add_i32 m0, s56, 0xe000
	ds_read_b128 v[230:233], v156 offset:7168
	global_load_lds_dwordx4 v136, s[2:3]
	s_waitcnt vmcnt(8)
	s_waitcnt lgkmcnt(0)
	s_barrier
	s_setprio 1
	v_mfma_f32_16x16x32_bf16 v[124:127], v[140:143], v[184:187], v[124:127]
	v_mfma_f32_16x16x32_bf16 v[120:123], v[160:163], v[184:187], v[120:123]
	v_mfma_f32_16x16x32_bf16 v[108:111], v[140:143], v[204:207], v[108:111]
	v_mfma_f32_16x16x32_bf16 v[104:107], v[160:163], v[204:207], v[104:107]
	v_mfma_f32_16x16x32_bf16 v[92:95], v[140:143], v[212:215], v[92:95]
	v_mfma_f32_16x16x32_bf16 v[88:91], v[160:163], v[212:215], v[88:91]
	v_mfma_f32_16x16x32_bf16 v[76:79], v[140:143], v[226:229], v[76:79]
	v_mfma_f32_16x16x32_bf16 v[72:75], v[160:163], v[226:229], v[72:75]
	v_mfma_f32_16x16x32_bf16 v[124:127], v[144:147], v[200:203], v[124:127]
	v_mfma_f32_16x16x32_bf16 v[120:123], v[164:167], v[200:203], v[120:123]
	v_mfma_f32_16x16x32_bf16 v[108:111], v[144:147], v[208:211], v[108:111]
	v_mfma_f32_16x16x32_bf16 v[104:107], v[164:167], v[208:211], v[104:107]
	v_mfma_f32_16x16x32_bf16 v[92:95], v[144:147], v[216:219], v[92:95]
	v_mfma_f32_16x16x32_bf16 v[88:91], v[164:167], v[216:219], v[88:91]
	v_mfma_f32_16x16x32_bf16 v[76:79], v[144:147], v[230:233], v[76:79]
	v_mfma_f32_16x16x32_bf16 v[72:75], v[164:167], v[230:233], v[72:75]
	s_setprio 0
	s_setprio 1
	v_mfma_f32_16x16x32_bf16 v[116:119], v[168:171], v[184:187], v[116:119]
	v_mfma_f32_16x16x32_bf16 v[112:115], v[176:179], v[184:187], v[112:115]
	v_mfma_f32_16x16x32_bf16 v[100:103], v[168:171], v[204:207], v[100:103]
	v_mfma_f32_16x16x32_bf16 v[96:99], v[176:179], v[204:207], v[96:99]
	v_mfma_f32_16x16x32_bf16 v[84:87], v[168:171], v[212:215], v[84:87]
	v_mfma_f32_16x16x32_bf16 v[80:83], v[176:179], v[212:215], v[80:83]
	v_mfma_f32_16x16x32_bf16 v[68:71], v[168:171], v[226:229], v[68:71]
	v_mfma_f32_16x16x32_bf16 v[64:67], v[176:179], v[226:229], v[64:67]
	v_mfma_f32_16x16x32_bf16 v[116:119], v[172:175], v[200:203], v[116:119]
	v_mfma_f32_16x16x32_bf16 v[112:115], v[180:183], v[200:203], v[112:115]
	v_mfma_f32_16x16x32_bf16 v[100:103], v[172:175], v[208:211], v[100:103]
	v_mfma_f32_16x16x32_bf16 v[96:99], v[180:183], v[208:211], v[96:99]
	v_mfma_f32_16x16x32_bf16 v[84:87], v[172:175], v[216:219], v[84:87]
	v_mfma_f32_16x16x32_bf16 v[80:83], v[180:183], v[216:219], v[80:83]
	v_mfma_f32_16x16x32_bf16 v[68:71], v[172:175], v[230:233], v[68:71]
	v_mfma_f32_16x16x32_bf16 v[64:67], v[180:183], v[230:233], v[64:67]
	s_setprio 0
	s_barrier
	s_add_i32 s66, s66, s49
	s_mov_b32 m0, s66
	ds_read_b128 v[184:187], v156 offset:16384
	ds_read_b128 v[200:203], v156 offset:17408
	ds_read_b128 v[204:207], v156 offset:18432
	ds_read_b128 v[208:211], v156 offset:19456
	ds_read_b128 v[212:215], v156 offset:20480
	global_load_lds_dwordx4 v132, s[12:13]
	s_add_i32 m0, s66, 0x2000
	s_add_u32 s66, s12, 0x40000
	s_addc_u32 s67, s13, 0
	s_add_i32 s68, s68, s49
	global_load_lds_dwordx4 v128, s[12:13]
	s_mov_b32 m0, s68
	s_mov_b64 s[100:101], s[14:15]
	global_load_lds_dwordx4 v132, s[66:67]
	s_add_i32 m0, s68, 0x2000
	ds_read_b128 v[216:219], v156 offset:21504
	global_load_lds_dwordx4 v128, s[66:67]
	s_mov_b32 m0, s56
	ds_read_b128 v[226:229], v156 offset:22528
	global_load_lds_dwordx4 v134, s[100:101]
	s_mov_b32 m0, s57
	ds_read_b128 v[230:233], v156 offset:23552
	global_load_lds_dwordx4 v130, s[100:101]
	s_waitcnt vmcnt(8)
	s_waitcnt lgkmcnt(0)
	s_barrier
	s_setprio 1
	v_mfma_f32_16x16x32_bf16 v[60:63], v[140:143], v[184:187], v[60:63]
	v_mfma_f32_16x16x32_bf16 v[56:59], v[160:163], v[184:187], v[56:59]
	v_mfma_f32_16x16x32_bf16 v[44:47], v[140:143], v[204:207], v[44:47]
	v_mfma_f32_16x16x32_bf16 v[40:43], v[160:163], v[204:207], v[40:43]
	v_mfma_f32_16x16x32_bf16 v[28:31], v[140:143], v[212:215], v[28:31]
	v_mfma_f32_16x16x32_bf16 v[24:27], v[160:163], v[212:215], v[24:27]
	v_mfma_f32_16x16x32_bf16 v[12:15], v[140:143], v[226:229], v[12:15]
	v_mfma_f32_16x16x32_bf16 v[8:11], v[160:163], v[226:229], v[8:11]
	v_mfma_f32_16x16x32_bf16 v[60:63], v[144:147], v[200:203], v[60:63]
	v_mfma_f32_16x16x32_bf16 v[56:59], v[164:167], v[200:203], v[56:59]
	v_mfma_f32_16x16x32_bf16 v[44:47], v[144:147], v[208:211], v[44:47]
	v_mfma_f32_16x16x32_bf16 v[40:43], v[164:167], v[208:211], v[40:43]
	v_mfma_f32_16x16x32_bf16 v[28:31], v[144:147], v[216:219], v[28:31]
	v_mfma_f32_16x16x32_bf16 v[24:27], v[164:167], v[216:219], v[24:27]
	v_mfma_f32_16x16x32_bf16 v[12:15], v[144:147], v[230:233], v[12:15]
	v_mfma_f32_16x16x32_bf16 v[8:11], v[164:167], v[230:233], v[8:11]
	s_setprio 0
	s_setprio 1
	v_mfma_f32_16x16x32_bf16 v[52:55], v[168:171], v[184:187], v[52:55]
	v_mfma_f32_16x16x32_bf16 v[48:51], v[176:179], v[184:187], v[48:51]
	v_mfma_f32_16x16x32_bf16 v[36:39], v[168:171], v[204:207], v[36:39]
	v_mfma_f32_16x16x32_bf16 v[32:35], v[176:179], v[204:207], v[32:35]
	v_mfma_f32_16x16x32_bf16 v[20:23], v[168:171], v[212:215], v[20:23]
	v_mfma_f32_16x16x32_bf16 v[16:19], v[176:179], v[212:215], v[16:19]
	v_mfma_f32_16x16x32_bf16 v[4:7], v[168:171], v[226:229], v[4:7]
	v_mfma_f32_16x16x32_bf16 v[0:3], v[176:179], v[226:229], v[0:3]
	v_mfma_f32_16x16x32_bf16 v[52:55], v[172:175], v[200:203], v[52:55]
	v_mfma_f32_16x16x32_bf16 v[48:51], v[180:183], v[200:203], v[48:51]
	v_mfma_f32_16x16x32_bf16 v[36:39], v[172:175], v[208:211], v[36:39]
	v_mfma_f32_16x16x32_bf16 v[32:35], v[180:183], v[208:211], v[32:35]
	v_mfma_f32_16x16x32_bf16 v[20:23], v[172:175], v[216:219], v[20:23]
	v_mfma_f32_16x16x32_bf16 v[16:19], v[180:183], v[216:219], v[16:19]
	v_mfma_f32_16x16x32_bf16 v[4:7], v[172:175], v[230:233], v[4:7]
	v_mfma_f32_16x16x32_bf16 v[0:3], v[180:183], v[230:233], v[0:3]
	s_setprio 0
	s_barrier
; #define PG8_STAGE(bufoff, gbase, voff) do { _Pragma("unroll") for (int _i = 0; _i < 2; ++_i) \
;         __builtin_amdgcn_global_load_lds((const unsigned*)((const char*)(gbase) + (voff)[_i]), (PG8_LAS unsigned*)(lds + (bufoff) + ldsw + _i * 8192), 16, 0, 0); } while (0)
; #define PG8_LDA(dst, b, h) do { _Pragma("unroll") for (int m = 0; m < 4; ++m) _Pragma("unroll") for (int k = 0; k < 2; ++k) dst[m][k] = *(const PG8_LAS bf16x8*)(lds + PG8_SA(b, h) + aoff + m * 2048 + k * 1024); } while (0)
; #define PG8_LDB(dst, b, h) do { _Pragma("unroll") for (int n = 0; n < 2; ++n) _Pragma("unroll") for (int k = 0; k < 2; ++k) dst[n][k] = *(const PG8_LAS bf16x8*)(lds + PG8_SB(b, h) + boff + n * 2048 + k * 1024); } while (0)
; #define PG8_MMA(ai, bj, At, Bt) do { __builtin_amdgcn_s_setprio(1); _Pragma("unroll") for (int m = 0; m < 4; ++m) _Pragma("unroll") for (int n = 0; n < 2; ++n) _Pragma("unroll") for (int k = 0; k < 2; ++k) \
;         acc[ai][bj][m][n] = __builtin_amdgcn_mfma_f32_16x16x32_bf16(Bt[n][k], At[m][k], acc[ai][bj][m][n], 0, 0, 0); __builtin_amdgcn_s_setprio(0); } while (0)
; #define PG8_WAIT_V(n) asm volatile("s_waitcnt vmcnt(" #n ")" ::: "memory")
; #define PG8_WAIT_L(n) asm volatile("s_waitcnt lgkmcnt(" #n ")" ::: "memory")
; #define PG8_BAR __builtin_amdgcn_s_barrier()
; #define PG8_SCHED __builtin_amdgcn_sched_barrier(0)
; template <class Epi, class Sched, bool ALIGN_EPI = false, bool SP2 = false>
; __device__ __forceinline__ void gemm_phase(PG8_LAS unsigned char* lds, const Gemm g, const Sched& S, const Epi& E, int tid_in) {
;     ...
;             PG8_LDB(B0, 1, 0); PG8_LDB(B1, 1, 1); PG8_SCHED; PG8_LDA(At, 1, 0); PG8_STAGE(PG8_SA(0, 1), a2 + hstepA, voffA);
;             PG8_WAIT_V(8); PG8_WAIT_L(0); PG8_BAR; PG8_MMA(0, 0, At, B0); PG8_MMA(0, 1, At, B1); PG8_BAR; PG8_SCHED;
;             PG8_LDA(At, 1, 1); PG8_STAGE(PG8_SB(1, 0), b3, voffB); PG8_STAGE(PG8_SB(1, 1), b3 + hstep, voffB); PG8_STAGE(PG8_SA(1, 0), a3, voffA);
;             PG8_WAIT_V(8); PG8_WAIT_L(0); PG8_BAR; PG8_MMA(1, 0, At, B0); PG8_MMA(1, 1, At, B1); PG8_BAR; PG8_SCHED;
	s_add_i32 s66, 0, 0x18000
	v_add_u32_e32 v157, s66, v151
	s_add_i32 s67, 0, 0x1c000
	ds_read_b128 v[140:143], v157
	ds_read_b128 v[144:147], v157 offset:1024
	ds_read_b128 v[160:163], v157 offset:2048
	ds_read_b128 v[164:167], v157 offset:3072
	v_add_u32_e32 v157, s67, v151
	ds_read_b128 v[168:171], v157
	ds_read_b128 v[172:175], v157 offset:1024
	ds_read_b128 v[176:179], v157 offset:2048
	ds_read_b128 v[180:183], v157 offset:3072
	s_add_u32 s14, s14, 0x40000
	s_addc_u32 s15, s15, 0
	s_mov_b32 m0, s58
	ds_read_b128 v[184:187], v156 offset:32768
	ds_read_b128 v[200:203], v156 offset:33792
	ds_read_b128 v[204:207], v156 offset:34816
	ds_read_b128 v[208:211], v156 offset:35840
	ds_read_b128 v[212:215], v156 offset:36864
	ds_read_b128 v[216:219], v156 offset:37888
	ds_read_b128 v[226:229], v156 offset:38912
	global_load_lds_dwordx4 v134, s[14:15]
	s_mov_b32 m0, s59
	ds_read_b128 v[230:233], v156 offset:39936
	global_load_lds_dwordx4 v130, s[14:15]
	s_waitcnt vmcnt(8)
	s_waitcnt lgkmcnt(0)
	s_barrier
	s_setprio 1
	v_mfma_f32_16x16x32_bf16 v[124:127], v[140:143], v[184:187], v[124:127]
	v_mfma_f32_16x16x32_bf16 v[120:123], v[160:163], v[184:187], v[120:123]
	v_mfma_f32_16x16x32_bf16 v[108:111], v[140:143], v[204:207], v[108:111]
	v_mfma_f32_16x16x32_bf16 v[104:107], v[160:163], v[204:207], v[104:107]
	v_mfma_f32_16x16x32_bf16 v[92:95], v[140:143], v[212:215], v[92:95]
	v_mfma_f32_16x16x32_bf16 v[88:91], v[160:163], v[212:215], v[88:91]
	v_mfma_f32_16x16x32_bf16 v[76:79], v[140:143], v[226:229], v[76:79]
	v_mfma_f32_16x16x32_bf16 v[72:75], v[160:163], v[226:229], v[72:75]
	v_mfma_f32_16x16x32_bf16 v[124:127], v[144:147], v[200:203], v[124:127]
	v_mfma_f32_16x16x32_bf16 v[120:123], v[164:167], v[200:203], v[120:123]
	v_mfma_f32_16x16x32_bf16 v[108:111], v[144:147], v[208:211], v[108:111]
	v_mfma_f32_16x16x32_bf16 v[104:107], v[164:167], v[208:211], v[104:107]
	v_mfma_f32_16x16x32_bf16 v[92:95], v[144:147], v[216:219], v[92:95]
	v_mfma_f32_16x16x32_bf16 v[88:91], v[164:167], v[216:219], v[88:91]
	v_mfma_f32_16x16x32_bf16 v[76:79], v[144:147], v[230:233], v[76:79]
	v_mfma_f32_16x16x32_bf16 v[72:75], v[164:167], v[230:233], v[72:75]
	s_setprio 0
	s_setprio 1
	v_mfma_f32_16x16x32_bf16 v[116:119], v[168:171], v[184:187], v[116:119]
	v_mfma_f32_16x16x32_bf16 v[112:115], v[176:179], v[184:187], v[112:115]
	v_mfma_f32_16x16x32_bf16 v[100:103], v[168:171], v[204:207], v[100:103]
	v_mfma_f32_16x16x32_bf16 v[96:99], v[176:179], v[204:207], v[96:99]
	v_mfma_f32_16x16x32_bf16 v[84:87], v[168:171], v[212:215], v[84:87]
	v_mfma_f32_16x16x32_bf16 v[80:83], v[176:179], v[212:215], v[80:83]
	v_mfma_f32_16x16x32_bf16 v[68:71], v[168:171], v[226:229], v[68:71]
	v_mfma_f32_16x16x32_bf16 v[64:67], v[176:179], v[226:229], v[64:67]
	v_mfma_f32_16x16x32_bf16 v[116:119], v[172:175], v[200:203], v[116:119]
	v_mfma_f32_16x16x32_bf16 v[112:115], v[180:183], v[200:203], v[112:115]
	v_mfma_f32_16x16x32_bf16 v[100:103], v[172:175], v[208:211], v[100:103]
	v_mfma_f32_16x16x32_bf16 v[96:99], v[180:183], v[208:211], v[96:99]
	v_mfma_f32_16x16x32_bf16 v[84:87], v[172:175], v[216:219], v[84:87]
	v_mfma_f32_16x16x32_bf16 v[80:83], v[180:183], v[216:219], v[80:83]
	v_mfma_f32_16x16x32_bf16 v[68:71], v[172:175], v[230:233], v[68:71]
	v_mfma_f32_16x16x32_bf16 v[64:67], v[180:183], v[230:233], v[64:67]
	s_setprio 0
	s_barrier
	s_add_i32 s14, s66, s49
	s_mov_b32 m0, s14
	ds_read_b128 v[184:187], v156 offset:49152
	ds_read_b128 v[200:203], v156 offset:50176
	ds_read_b128 v[204:207], v156 offset:51200
	ds_read_b128 v[208:211], v156 offset:52224
	s_add_u32 s12, s12, 0x80
	s_addc_u32 s13, s13, 0
	global_load_lds_dwordx4 v132, s[12:13]
	s_add_i32 m0, s14, 0x2000
	ds_read_b128 v[212:215], v156 offset:53248
	global_load_lds_dwordx4 v128, s[12:13]
	s_add_u32 s12, s12, 0x40000
	s_addc_u32 s13, s13, 0
	s_add_i32 s14, s67, s49
	s_mov_b32 m0, s14
	ds_read_b128 v[216:219], v156 offset:54272
	global_load_lds_dwordx4 v132, s[12:13]
	s_add_i32 m0, s14, 0x2000
	ds_read_b128 v[226:229], v156 offset:55296
	global_load_lds_dwordx4 v128, s[12:13]
	s_mov_b32 m0, s61
	s_nop 0
	s_add_u32 s100, s100, 0x80
	s_addc_u32 s101, s101, 0
	global_load_lds_dwordx4 v134, s[100:101]
	s_mov_b32 m0, s62
	ds_read_b128 v[230:233], v156 offset:56320
	global_load_lds_dwordx4 v130, s[100:101]
	s_waitcnt vmcnt(8)
	s_waitcnt lgkmcnt(0)
	s_barrier
	s_setprio 1
	v_mfma_f32_16x16x32_bf16 v[60:63], v[140:143], v[184:187], v[60:63]
	v_mfma_f32_16x16x32_bf16 v[56:59], v[160:163], v[184:187], v[56:59]
	v_mfma_f32_16x16x32_bf16 v[44:47], v[140:143], v[204:207], v[44:47]
	v_mfma_f32_16x16x32_bf16 v[40:43], v[160:163], v[204:207], v[40:43]
	v_mfma_f32_16x16x32_bf16 v[28:31], v[140:143], v[212:215], v[28:31]
	v_mfma_f32_16x16x32_bf16 v[24:27], v[160:163], v[212:215], v[24:27]
	v_mfma_f32_16x16x32_bf16 v[12:15], v[140:143], v[226:229], v[12:15]
	v_mfma_f32_16x16x32_bf16 v[8:11], v[160:163], v[226:229], v[8:11]
	v_mfma_f32_16x16x32_bf16 v[60:63], v[144:147], v[200:203], v[60:63]
	v_mfma_f32_16x16x32_bf16 v[56:59], v[164:167], v[200:203], v[56:59]
	v_mfma_f32_16x16x32_bf16 v[44:47], v[144:147], v[208:211], v[44:47]
	v_mfma_f32_16x16x32_bf16 v[40:43], v[164:167], v[208:211], v[40:43]
	v_mfma_f32_16x16x32_bf16 v[28:31], v[144:147], v[216:219], v[28:31]
	v_mfma_f32_16x16x32_bf16 v[24:27], v[164:167], v[216:219], v[24:27]
	v_mfma_f32_16x16x32_bf16 v[12:15], v[144:147], v[230:233], v[12:15]
	v_mfma_f32_16x16x32_bf16 v[8:11], v[164:167], v[230:233], v[8:11]
	s_setprio 0
	s_setprio 1
	v_mfma_f32_16x16x32_bf16 v[52:55], v[168:171], v[184:187], v[52:55]
	v_mfma_f32_16x16x32_bf16 v[48:51], v[176:179], v[184:187], v[48:51]
	v_mfma_f32_16x16x32_bf16 v[36:39], v[168:171], v[204:207], v[36:39]
	v_mfma_f32_16x16x32_bf16 v[32:35], v[176:179], v[204:207], v[32:35]
	v_mfma_f32_16x16x32_bf16 v[20:23], v[168:171], v[212:215], v[20:23]
	v_mfma_f32_16x16x32_bf16 v[16:19], v[176:179], v[212:215], v[16:19]
	v_mfma_f32_16x16x32_bf16 v[4:7], v[168:171], v[226:229], v[4:7]
	v_mfma_f32_16x16x32_bf16 v[0:3], v[176:179], v[226:229], v[0:3]
	v_mfma_f32_16x16x32_bf16 v[52:55], v[172:175], v[200:203], v[52:55]
	v_mfma_f32_16x16x32_bf16 v[48:51], v[180:183], v[200:203], v[48:51]
	v_mfma_f32_16x16x32_bf16 v[36:39], v[172:175], v[208:211], v[36:39]
	v_mfma_f32_16x16x32_bf16 v[32:35], v[180:183], v[208:211], v[32:35]
	v_mfma_f32_16x16x32_bf16 v[20:23], v[172:175], v[216:219], v[20:23]
	v_mfma_f32_16x16x32_bf16 v[16:19], v[180:183], v[216:219], v[16:19]
	v_mfma_f32_16x16x32_bf16 v[4:7], v[172:175], v[230:233], v[4:7]
	v_mfma_f32_16x16x32_bf16 v[0:3], v[180:183], v[230:233], v[0:3]
	s_setprio 0
	s_barrier
	s_add_i32 s65, s65, 2
	s_add_u32 s51, s51, 0x100
	s_addc_u32 s64, s64, 0
	s_add_u32 s2, s2, 0x100
	s_addc_u32 s3, s3, 0
	s_cmp_gt_u32 s65, 13
	s_cbranch_scc0 .LBB0_526
	s_and_b64 vcc, exec, s[34:35]
	s_cbranch_vccz .LBB0_529
	s_barrier

; #define PG8_STAGE(bufoff, gbase, voff) do { _Pragma("unroll") for (int _i = 0; _i < 2; ++_i) \
;         __builtin_amdgcn_global_load_lds((const unsigned*)((const char*)(gbase) + (voff)[_i]), (PG8_LAS unsigned*)(lds + (bufoff) + ldsw + _i * 8192), 16, 0, 0); } while (0)
; #define PG8_LDA(dst, b, h) do { _Pragma("unroll") for (int m = 0; m < 4; ++m) _Pragma("unroll") for (int k = 0; k < 2; ++k) dst[m][k] = *(const PG8_LAS bf16x8*)(lds + PG8_SA(b, h) + aoff + m * 2048 + k * 1024); } while (0)
; #define PG8_LDB(dst, b, h) do { _Pragma("unroll") for (int n = 0; n < 2; ++n) _Pragma("unroll") for (int k = 0; k < 2; ++k) dst[n][k] = *(const PG8_LAS bf16x8*)(lds + PG8_SB(b, h) + boff + n * 2048 + k * 1024); } while (0)
; #define PG8_MMA(ai, bj, At, Bt) do { __builtin_amdgcn_s_setprio(1); _Pragma("unroll") for (int m = 0; m < 4; ++m) _Pragma("unroll") for (int n = 0; n < 2; ++n) _Pragma("unroll") for (int k = 0; k < 2; ++k) \
;         acc[ai][bj][m][n] = __builtin_amdgcn_mfma_f32_16x16x32_bf16(Bt[n][k], At[m][k], acc[ai][bj][m][n], 0, 0, 0); __builtin_amdgcn_s_setprio(0); } while (0)
; #define PG8_WAIT_V(n) asm volatile("s_waitcnt vmcnt(" #n ")" ::: "memory")
; #define PG8_WAIT_L(n) asm volatile("s_waitcnt lgkmcnt(" #n ")" ::: "memory")
; template <class Epi, class Sched, bool ALIGN_EPI = false, bool SP2 = false>
; __device__ __forceinline__ void gemm_phase(PG8_LAS unsigned char* lds, const Gemm g, const Sched& S, const Epi& E, int tid_in) {
;     ...
;             const bool last = (t == nt - 2);
;             const char* a1 = cA + (size_t)(t + 1) * kstep;
;             const char* a2 = last ? nA : cA + (size_t)(t + 2) * kstep; const char* b2 = last ? nB : cB + (size_t)(t + 2) * kstep;
;             const char* a3 = a2 + kstep; const char* b3 = b2 + kstep;
;             if (last && has_next) S.a_ready(nxt);
;             if constexpr (SP2) {
;             PG8_LDB(B0, 0, 0); PG8_LDB(B1, 0, 1); PG8_SCHED; PG8_LDA(At, 0, 0); PG8_STAGE(PG8_SA(1, 1), a1 + hstepA, voffA);
;             PG8_WAIT_V(8); PG8_WAIT_L(0); PG8_BAR; PG8_MMA(0, 0, At, B0); PG8_MMA(0, 1, At, B1); PG8_BAR; PG8_SCHED;
;             PG8_LDA(At, 0, 1); PG8_STAGE(PG8_SB(0, 0), b2, voffB); PG8_STAGE(PG8_SB(0, 1), b2 + hstep, voffB); PG8_STAGE(PG8_SA(0, 0), a2, voffA);
;             PG8_WAIT_V(8); PG8_WAIT_L(0); PG8_BAR; PG8_MMA(1, 0, At, B0); PG8_MMA(1, 1, At, B1); PG8_BAR; PG8_SCHED;
.LBB0_691:
	s_add_u32 s28, s26, 0xfffc0080
	s_addc_u32 s29, s27, -1
	s_add_i32 s57, 0, 0x10000
	s_cmp_eq_u32 s56, 12
	s_cselect_b32 s31, s15, s29
	s_cselect_b32 s30, s52, s28
	v_add_u32_e32 v147, s57, v145
	s_cselect_b32 s29, s13, s55
	s_cselect_b32 s28, s53, s54
	s_add_i32 s60, 0, 0x14000
	ds_read_b128 v[140:143], v147
	ds_read_b128 v[148:151], v147 offset:1024
	ds_read_b128 v[152:155], v147 offset:2048
	ds_read_b128 v[156:159], v147 offset:3072
	v_add_u32_e32 v147, s60, v145
	ds_read_b128 v[160:163], v147
	ds_read_b128 v[164:167], v147 offset:1024
	ds_read_b128 v[168:171], v147 offset:2048
	ds_read_b128 v[172:175], v147 offset:3072
	s_add_i32 m0, s42, 0xc000
	ds_read_b128 v[176:179], v146
	ds_read_b128 v[180:183], v146 offset:1024
	ds_read_b128 v[184:187], v146 offset:2048
	ds_read_b128 v[200:203], v146 offset:3072
	ds_read_b128 v[204:207], v146 offset:4096
	ds_read_b128 v[208:211], v146 offset:5120
	ds_read_b128 v[212:215], v146 offset:6144
	global_load_lds_dwordx4 v138, s[26:27]
	s_add_i32 m0, s42, 0xe000
	ds_read_b128 v[216:219], v146 offset:7168
	global_load_lds_dwordx4 v136, s[26:27]
	s_waitcnt vmcnt(8)
	s_waitcnt lgkmcnt(0)
	s_barrier
	s_setprio 1
	v_mfma_f32_16x16x32_bf16 v[124:127], v[140:143], v[176:179], v[124:127]
	v_mfma_f32_16x16x32_bf16 v[120:123], v[152:155], v[176:179], v[120:123]
	v_mfma_f32_16x16x32_bf16 v[108:111], v[140:143], v[184:187], v[108:111]
	v_mfma_f32_16x16x32_bf16 v[104:107], v[152:155], v[184:187], v[104:107]
	v_mfma_f32_16x16x32_bf16 v[92:95], v[140:143], v[204:207], v[92:95]
	v_mfma_f32_16x16x32_bf16 v[88:91], v[152:155], v[204:207], v[88:91]
	v_mfma_f32_16x16x32_bf16 v[76:79], v[140:143], v[212:215], v[76:79]
	v_mfma_f32_16x16x32_bf16 v[72:75], v[152:155], v[212:215], v[72:75]
	v_mfma_f32_16x16x32_bf16 v[124:127], v[148:151], v[180:183], v[124:127]
	v_mfma_f32_16x16x32_bf16 v[120:123], v[156:159], v[180:183], v[120:123]
	v_mfma_f32_16x16x32_bf16 v[108:111], v[148:151], v[200:203], v[108:111]
	v_mfma_f32_16x16x32_bf16 v[104:107], v[156:159], v[200:203], v[104:107]
	v_mfma_f32_16x16x32_bf16 v[92:95], v[148:151], v[208:211], v[92:95]
	v_mfma_f32_16x16x32_bf16 v[88:91], v[156:159], v[208:211], v[88:91]
	v_mfma_f32_16x16x32_bf16 v[76:79], v[148:151], v[216:219], v[76:79]
	v_mfma_f32_16x16x32_bf16 v[72:75], v[156:159], v[216:219], v[72:75]
	s_setprio 0
	s_setprio 1
	v_mfma_f32_16x16x32_bf16 v[116:119], v[160:163], v[176:179], v[116:119]
	v_mfma_f32_16x16x32_bf16 v[112:115], v[168:171], v[176:179], v[112:115]
	v_mfma_f32_16x16x32_bf16 v[100:103], v[160:163], v[184:187], v[100:103]
	v_mfma_f32_16x16x32_bf16 v[96:99], v[168:171], v[184:187], v[96:99]
	v_mfma_f32_16x16x32_bf16 v[84:87], v[160:163], v[204:207], v[84:87]
	v_mfma_f32_16x16x32_bf16 v[80:83], v[168:171], v[204:207], v[80:83]
	v_mfma_f32_16x16x32_bf16 v[68:71], v[160:163], v[212:215], v[68:71]
	v_mfma_f32_16x16x32_bf16 v[64:67], v[168:171], v[212:215], v[64:67]
	v_mfma_f32_16x16x32_bf16 v[116:119], v[164:167], v[180:183], v[116:119]
	v_mfma_f32_16x16x32_bf16 v[112:115], v[172:175], v[180:183], v[112:115]
	v_mfma_f32_16x16x32_bf16 v[100:103], v[164:167], v[200:203], v[100:103]
	v_mfma_f32_16x16x32_bf16 v[96:99], v[172:175], v[200:203], v[96:99]
	v_mfma_f32_16x16x32_bf16 v[84:87], v[164:167], v[208:211], v[84:87]
	v_mfma_f32_16x16x32_bf16 v[80:83], v[172:175], v[208:211], v[80:83]
	v_mfma_f32_16x16x32_bf16 v[68:71], v[164:167], v[216:219], v[68:71]
	v_mfma_f32_16x16x32_bf16 v[64:67], v[172:175], v[216:219], v[64:67]
	s_setprio 0
	s_barrier
	s_add_i32 s57, s57, s41
	s_mov_b32 m0, s57
	ds_read_b128 v[176:179], v146 offset:16384
	ds_read_b128 v[180:183], v146 offset:17408
	ds_read_b128 v[184:187], v146 offset:18432
	ds_read_b128 v[200:203], v146 offset:19456
	ds_read_b128 v[204:207], v146 offset:20480
	global_load_lds_dwordx4 v132, s[28:29]
	s_add_i32 m0, s57, 0x2000
	s_add_u32 s58, s28, 0x40000
	s_addc_u32 s59, s29, 0
	s_add_i32 s57, s60, s41
	global_load_lds_dwordx4 v128, s[28:29]
	s_mov_b32 m0, s57
	s_mov_b64 s[100:101], s[30:31]
	global_load_lds_dwordx4 v132, s[58:59]
	s_add_i32 m0, s57, 0x2000
	ds_read_b128 v[208:211], v146 offset:21504
	global_load_lds_dwordx4 v128, s[58:59]
	s_mov_b32 m0, s42
	ds_read_b128 v[212:215], v146 offset:22528
	global_load_lds_dwordx4 v134, s[100:101]
	s_mov_b32 m0, s43
	ds_read_b128 v[216:219], v146 offset:23552
	global_load_lds_dwordx4 v130, s[100:101]
	s_waitcnt vmcnt(8)
	s_waitcnt lgkmcnt(0)
	s_barrier
	s_setprio 1
	v_mfma_f32_16x16x32_bf16 v[60:63], v[140:143], v[176:179], v[60:63]
	v_mfma_f32_16x16x32_bf16 v[56:59], v[152:155], v[176:179], v[56:59]
	v_mfma_f32_16x16x32_bf16 v[44:47], v[140:143], v[184:187], v[44:47]
	v_mfma_f32_16x16x32_bf16 v[40:43], v[152:155], v[184:187], v[40:43]
	v_mfma_f32_16x16x32_bf16 v[28:31], v[140:143], v[204:207], v[28:31]
	v_mfma_f32_16x16x32_bf16 v[24:27], v[152:155], v[204:207], v[24:27]
	v_mfma_f32_16x16x32_bf16 v[12:15], v[140:143], v[212:215], v[12:15]
	v_mfma_f32_16x16x32_bf16 v[8:11], v[152:155], v[212:215], v[8:11]
	v_mfma_f32_16x16x32_bf16 v[60:63], v[148:151], v[180:183], v[60:63]
	v_mfma_f32_16x16x32_bf16 v[56:59], v[156:159], v[180:183], v[56:59]
	v_mfma_f32_16x16x32_bf16 v[44:47], v[148:151], v[200:203], v[44:47]
	v_mfma_f32_16x16x32_bf16 v[40:43], v[156:159], v[200:203], v[40:43]
	v_mfma_f32_16x16x32_bf16 v[28:31], v[148:151], v[208:211], v[28:31]
	v_mfma_f32_16x16x32_bf16 v[24:27], v[156:159], v[208:211], v[24:27]
	v_mfma_f32_16x16x32_bf16 v[12:15], v[148:151], v[216:219], v[12:15]
	v_mfma_f32_16x16x32_bf16 v[8:11], v[156:159], v[216:219], v[8:11]
	s_setprio 0
	s_setprio 1
	v_mfma_f32_16x16x32_bf16 v[52:55], v[160:163], v[176:179], v[52:55]
	v_mfma_f32_16x16x32_bf16 v[48:51], v[168:171], v[176:179], v[48:51]
	v_mfma_f32_16x16x32_bf16 v[36:39], v[160:163], v[184:187], v[36:39]
	v_mfma_f32_16x16x32_bf16 v[32:35], v[168:171], v[184:187], v[32:35]
	v_mfma_f32_16x16x32_bf16 v[20:23], v[160:163], v[204:207], v[20:23]
	v_mfma_f32_16x16x32_bf16 v[16:19], v[168:171], v[204:207], v[16:19]
	v_mfma_f32_16x16x32_bf16 v[4:7], v[160:163], v[212:215], v[4:7]
	v_mfma_f32_16x16x32_bf16 v[0:3], v[168:171], v[212:215], v[0:3]
	v_mfma_f32_16x16x32_bf16 v[52:55], v[164:167], v[180:183], v[52:55]
	v_mfma_f32_16x16x32_bf16 v[48:51], v[172:175], v[180:183], v[48:51]
	v_mfma_f32_16x16x32_bf16 v[36:39], v[164:167], v[200:203], v[36:39]
	v_mfma_f32_16x16x32_bf16 v[32:35], v[172:175], v[200:203], v[32:35]
	v_mfma_f32_16x16x32_bf16 v[20:23], v[164:167], v[208:211], v[20:23]
	v_mfma_f32_16x16x32_bf16 v[16:19], v[172:175], v[208:211], v[16:19]
	v_mfma_f32_16x16x32_bf16 v[4:7], v[164:167], v[216:219], v[4:7]
	v_mfma_f32_16x16x32_bf16 v[0:3], v[172:175], v[216:219], v[0:3]
	s_setprio 0
	s_barrier
; #define PG8_STAGE(bufoff, gbase, voff) do { _Pragma("unroll") for (int _i = 0; _i < 2; ++_i) \
;         __builtin_amdgcn_global_load_lds((const unsigned*)((const char*)(gbase) + (voff)[_i]), (PG8_LAS unsigned*)(lds + (bufoff) + ldsw + _i * 8192), 16, 0, 0); } while (0)
; #define PG8_LDA(dst, b, h) do { _Pragma("unroll") for (int m = 0; m < 4; ++m) _Pragma("unroll") for (int k = 0; k < 2; ++k) dst[m][k] = *(const PG8_LAS bf16x8*)(lds + PG8_SA(b, h) + aoff + m * 2048 + k * 1024); } while (0)
; #define PG8_LDB(dst, b, h) do { _Pragma("unroll") for (int n = 0; n < 2; ++n) _Pragma("unroll") for (int k = 0; k < 2; ++k) dst[n][k] = *(const PG8_LAS bf16x8*)(lds + PG8_SB(b, h) + boff + n * 2048 + k * 1024); } while (0)
; #define PG8_MMA(ai, bj, At, Bt) do { __builtin_amdgcn_s_setprio(1); _Pragma("unroll") for (int m = 0; m < 4; ++m) _Pragma("unroll") for (int n = 0; n < 2; ++n) _Pragma("unroll") for (int k = 0; k < 2; ++k) \
;         acc[ai][bj][m][n] = __builtin_amdgcn_mfma_f32_16x16x32_bf16(Bt[n][k], At[m][k], acc[ai][bj][m][n], 0, 0, 0); __builtin_amdgcn_s_setprio(0); } while (0)
; #define PG8_WAIT_V(n) asm volatile("s_waitcnt vmcnt(" #n ")" ::: "memory")
; #define PG8_WAIT_L(n) asm volatile("s_waitcnt lgkmcnt(" #n ")" ::: "memory")
; #define PG8_BAR __builtin_amdgcn_s_barrier()
; #define PG8_SCHED __builtin_amdgcn_sched_barrier(0)
; template <class Epi, class Sched, bool ALIGN_EPI = false, bool SP2 = false>
; __device__ __forceinline__ void gemm_phase(PG8_LAS unsigned char* lds, const Gemm g, const Sched& S, const Epi& E, int tid_in) {
;     ...
;             PG8_LDB(B0, 1, 0); PG8_LDB(B1, 1, 1); PG8_SCHED; PG8_LDA(At, 1, 0); PG8_STAGE(PG8_SA(0, 1), a2 + hstepA, voffA);
;             PG8_WAIT_V(8); PG8_WAIT_L(0); PG8_BAR; PG8_MMA(0, 0, At, B0); PG8_MMA(0, 1, At, B1); PG8_BAR; PG8_SCHED;
;             PG8_LDA(At, 1, 1); PG8_STAGE(PG8_SB(1, 0), b3, voffB); PG8_STAGE(PG8_SB(1, 1), b3 + hstep, voffB); PG8_STAGE(PG8_SA(1, 0), a3, voffA);
;             PG8_WAIT_V(8); PG8_WAIT_L(0); PG8_BAR; PG8_MMA(1, 0, At, B0); PG8_MMA(1, 1, At, B1); PG8_BAR; PG8_SCHED;
	s_add_i32 s57, 0, 0x18000
	v_add_u32_e32 v147, s57, v145
	s_add_i32 s58, 0, 0x1c000
	ds_read_b128 v[140:143], v147
	ds_read_b128 v[148:151], v147 offset:1024
	ds_read_b128 v[152:155], v147 offset:2048
	ds_read_b128 v[156:159], v147 offset:3072
	v_add_u32_e32 v147, s58, v145
	ds_read_b128 v[160:163], v147
	ds_read_b128 v[164:167], v147 offset:1024
	ds_read_b128 v[168:171], v147 offset:2048
	ds_read_b128 v[172:175], v147 offset:3072
	s_add_u32 s30, s30, 0x40000
	s_addc_u32 s31, s31, 0
	s_mov_b32 m0, s44
	ds_read_b128 v[176:179], v146 offset:32768
	ds_read_b128 v[180:183], v146 offset:33792
	ds_read_b128 v[184:187], v146 offset:34816
	ds_read_b128 v[200:203], v146 offset:35840
	ds_read_b128 v[204:207], v146 offset:36864
	ds_read_b128 v[208:211], v146 offset:37888
	ds_read_b128 v[212:215], v146 offset:38912
	global_load_lds_dwordx4 v134, s[30:31]
	s_mov_b32 m0, s45
	ds_read_b128 v[216:219], v146 offset:39936
	global_load_lds_dwordx4 v130, s[30:31]
	s_waitcnt vmcnt(8)
	s_waitcnt lgkmcnt(0)
	s_barrier
	s_setprio 1
	v_mfma_f32_16x16x32_bf16 v[124:127], v[140:143], v[176:179], v[124:127]
	v_mfma_f32_16x16x32_bf16 v[120:123], v[152:155], v[176:179], v[120:123]
	v_mfma_f32_16x16x32_bf16 v[108:111], v[140:143], v[184:187], v[108:111]
	v_mfma_f32_16x16x32_bf16 v[104:107], v[152:155], v[184:187], v[104:107]
	v_mfma_f32_16x16x32_bf16 v[92:95], v[140:143], v[204:207], v[92:95]
	v_mfma_f32_16x16x32_bf16 v[88:91], v[152:155], v[204:207], v[88:91]
	v_mfma_f32_16x16x32_bf16 v[76:79], v[140:143], v[212:215], v[76:79]
	v_mfma_f32_16x16x32_bf16 v[72:75], v[152:155], v[212:215], v[72:75]
	v_mfma_f32_16x16x32_bf16 v[124:127], v[148:151], v[180:183], v[124:127]
	v_mfma_f32_16x16x32_bf16 v[120:123], v[156:159], v[180:183], v[120:123]
	v_mfma_f32_16x16x32_bf16 v[108:111], v[148:151], v[200:203], v[108:111]
	v_mfma_f32_16x16x32_bf16 v[104:107], v[156:159], v[200:203], v[104:107]
	v_mfma_f32_16x16x32_bf16 v[92:95], v[148:151], v[208:211], v[92:95]
	v_mfma_f32_16x16x32_bf16 v[88:91], v[156:159], v[208:211], v[88:91]
	v_mfma_f32_16x16x32_bf16 v[76:79], v[148:151], v[216:219], v[76:79]
	v_mfma_f32_16x16x32_bf16 v[72:75], v[156:159], v[216:219], v[72:75]
	s_setprio 0
	s_setprio 1
	v_mfma_f32_16x16x32_bf16 v[116:119], v[160:163], v[176:179], v[116:119]
	v_mfma_f32_16x16x32_bf16 v[112:115], v[168:171], v[176:179], v[112:115]
	v_mfma_f32_16x16x32_bf16 v[100:103], v[160:163], v[184:187], v[100:103]
	v_mfma_f32_16x16x32_bf16 v[96:99], v[168:171], v[184:187], v[96:99]
	v_mfma_f32_16x16x32_bf16 v[84:87], v[160:163], v[204:207], v[84:87]
	v_mfma_f32_16x16x32_bf16 v[80:83], v[168:171], v[204:207], v[80:83]
	v_mfma_f32_16x16x32_bf16 v[68:71], v[160:163], v[212:215], v[68:71]
	v_mfma_f32_16x16x32_bf16 v[64:67], v[168:171], v[212:215], v[64:67]
	v_mfma_f32_16x16x32_bf16 v[116:119], v[164:167], v[180:183], v[116:119]
	v_mfma_f32_16x16x32_bf16 v[112:115], v[172:175], v[180:183], v[112:115]
	v_mfma_f32_16x16x32_bf16 v[100:103], v[164:167], v[200:203], v[100:103]
	v_mfma_f32_16x16x32_bf16 v[96:99], v[172:175], v[200:203], v[96:99]
	v_mfma_f32_16x16x32_bf16 v[84:87], v[164:167], v[208:211], v[84:87]
	v_mfma_f32_16x16x32_bf16 v[80:83], v[172:175], v[208:211], v[80:83]
	v_mfma_f32_16x16x32_bf16 v[68:71], v[164:167], v[216:219], v[68:71]
	v_mfma_f32_16x16x32_bf16 v[64:67], v[172:175], v[216:219], v[64:67]
	s_setprio 0
	s_barrier
	s_add_i32 s30, s57, s41
	s_mov_b32 m0, s30
	ds_read_b128 v[176:179], v146 offset:49152
	ds_read_b128 v[180:183], v146 offset:50176
	ds_read_b128 v[184:187], v146 offset:51200
	ds_read_b128 v[200:203], v146 offset:52224
	s_add_u32 s28, s28, 0x80
	s_addc_u32 s29, s29, 0
	global_load_lds_dwordx4 v132, s[28:29]
	s_add_i32 m0, s30, 0x2000
	ds_read_b128 v[204:207], v146 offset:53248
	global_load_lds_dwordx4 v128, s[28:29]
	s_add_u32 s28, s28, 0x40000
	s_addc_u32 s29, s29, 0
	s_add_i32 s30, s58, s41
	s_mov_b32 m0, s30
	ds_read_b128 v[208:211], v146 offset:54272
	global_load_lds_dwordx4 v132, s[28:29]
	s_add_i32 m0, s30, 0x2000
	ds_read_b128 v[212:215], v146 offset:55296
	global_load_lds_dwordx4 v128, s[28:29]
	s_mov_b32 m0, s46
	s_nop 0
	s_add_u32 s100, s100, 0x80
	s_addc_u32 s101, s101, 0
	global_load_lds_dwordx4 v134, s[100:101]
	s_mov_b32 m0, s47
	ds_read_b128 v[216:219], v146 offset:56320
	global_load_lds_dwordx4 v130, s[100:101]
	s_waitcnt vmcnt(8)
	s_waitcnt lgkmcnt(0)
	s_barrier
	s_setprio 1
	v_mfma_f32_16x16x32_bf16 v[60:63], v[140:143], v[176:179], v[60:63]
	v_mfma_f32_16x16x32_bf16 v[56:59], v[152:155], v[176:179], v[56:59]
	v_mfma_f32_16x16x32_bf16 v[44:47], v[140:143], v[184:187], v[44:47]
	v_mfma_f32_16x16x32_bf16 v[40:43], v[152:155], v[184:187], v[40:43]
	v_mfma_f32_16x16x32_bf16 v[28:31], v[140:143], v[204:207], v[28:31]
	v_mfma_f32_16x16x32_bf16 v[24:27], v[152:155], v[204:207], v[24:27]
	v_mfma_f32_16x16x32_bf16 v[12:15], v[140:143], v[212:215], v[12:15]
	v_mfma_f32_16x16x32_bf16 v[8:11], v[152:155], v[212:215], v[8:11]
	v_mfma_f32_16x16x32_bf16 v[60:63], v[148:151], v[180:183], v[60:63]
	v_mfma_f32_16x16x32_bf16 v[56:59], v[156:159], v[180:183], v[56:59]
	v_mfma_f32_16x16x32_bf16 v[44:47], v[148:151], v[200:203], v[44:47]
	v_mfma_f32_16x16x32_bf16 v[40:43], v[156:159], v[200:203], v[40:43]
	v_mfma_f32_16x16x32_bf16 v[28:31], v[148:151], v[208:211], v[28:31]
	v_mfma_f32_16x16x32_bf16 v[24:27], v[156:159], v[208:211], v[24:27]
	v_mfma_f32_16x16x32_bf16 v[12:15], v[148:151], v[216:219], v[12:15]
	v_mfma_f32_16x16x32_bf16 v[8:11], v[156:159], v[216:219], v[8:11]
	s_setprio 0
	s_setprio 1
	v_mfma_f32_16x16x32_bf16 v[52:55], v[160:163], v[176:179], v[52:55]
	v_mfma_f32_16x16x32_bf16 v[48:51], v[168:171], v[176:179], v[48:51]
	v_mfma_f32_16x16x32_bf16 v[36:39], v[160:163], v[184:187], v[36:39]
	v_mfma_f32_16x16x32_bf16 v[32:35], v[168:171], v[184:187], v[32:35]
	v_mfma_f32_16x16x32_bf16 v[20:23], v[160:163], v[204:207], v[20:23]
	v_mfma_f32_16x16x32_bf16 v[16:19], v[168:171], v[204:207], v[16:19]
	v_mfma_f32_16x16x32_bf16 v[4:7], v[160:163], v[212:215], v[4:7]
	v_mfma_f32_16x16x32_bf16 v[0:3], v[168:171], v[212:215], v[0:3]
	v_mfma_f32_16x16x32_bf16 v[52:55], v[164:167], v[180:183], v[52:55]
	v_mfma_f32_16x16x32_bf16 v[48:51], v[172:175], v[180:183], v[48:51]
	v_mfma_f32_16x16x32_bf16 v[36:39], v[164:167], v[200:203], v[36:39]
	v_mfma_f32_16x16x32_bf16 v[32:35], v[172:175], v[200:203], v[32:35]
	v_mfma_f32_16x16x32_bf16 v[20:23], v[164:167], v[208:211], v[20:23]
	v_mfma_f32_16x16x32_bf16 v[16:19], v[172:175], v[208:211], v[16:19]
	v_mfma_f32_16x16x32_bf16 v[4:7], v[164:167], v[216:219], v[4:7]
	v_mfma_f32_16x16x32_bf16 v[0:3], v[172:175], v[216:219], v[0:3]
	s_setprio 0
	s_barrier
	s_add_i32 s56, s56, 2
	s_add_u32 s54, s54, 0x100
	s_addc_u32 s55, s55, 0
	s_add_u32 s26, s26, 0x100
	s_addc_u32 s27, s27, 0
	s_cmp_gt_u32 s56, 13
	s_cbranch_scc0 .LBB0_691
	v_readlane_b32 s56, v255, 17
	s_and_b64 vcc, exec, s[10:11]
	s_mov_b64 s[30:31], 0x10000600
	v_readlane_b32 s57, v255, 18
	v_readlane_b32 s58, v255, 19
	v_readlane_b32 s59, v255, 20
	s_cbranch_vccz .LBB0_694
	s_barrier

; #define PG8_STAGE(bufoff, gbase, voff) do { _Pragma("unroll") for (int _i = 0; _i < 2; ++_i) \
;         __builtin_amdgcn_global_load_lds((const unsigned*)((const char*)(gbase) + (voff)[_i]), (PG8_LAS unsigned*)(lds + (bufoff) + ldsw + _i * 8192), 16, 0, 0); } while (0)
; #define PG8_LDA(dst, b, h) do { _Pragma("unroll") for (int m = 0; m < 4; ++m) _Pragma("unroll") for (int k = 0; k < 2; ++k) dst[m][k] = *(const PG8_LAS bf16x8*)(lds + PG8_SA(b, h) + aoff + m * 2048 + k * 1024); } while (0)
; #define PG8_LDB(dst, b, h) do { _Pragma("unroll") for (int n = 0; n < 2; ++n) _Pragma("unroll") for (int k = 0; k < 2; ++k) dst[n][k] = *(const PG8_LAS bf16x8*)(lds + PG8_SB(b, h) + boff + n * 2048 + k * 1024); } while (0)
; #define PG8_MMA(ai, bj, At, Bt) do { __builtin_amdgcn_s_setprio(1); _Pragma("unroll") for (int m = 0; m < 4; ++m) _Pragma("unroll") for (int n = 0; n < 2; ++n) _Pragma("unroll") for (int k = 0; k < 2; ++k) \
;         acc[ai][bj][m][n] = __builtin_amdgcn_mfma_f32_16x16x32_bf16(Bt[n][k], At[m][k], acc[ai][bj][m][n], 0, 0, 0); __builtin_amdgcn_s_setprio(0); } while (0)
; #define PG8_WAIT_V(n) asm volatile("s_waitcnt vmcnt(" #n ")" ::: "memory")
; #define PG8_WAIT_L(n) asm volatile("s_waitcnt lgkmcnt(" #n ")" ::: "memory")
; template <class Epi, class Sched, bool ALIGN_EPI = false, bool SP2 = false>
; __device__ __forceinline__ void gemm_phase(PG8_LAS unsigned char* lds, const Gemm g, const Sched& S, const Epi& E, int tid_in) {
;     ...
;             const bool last = (t == nt - 2);
;             const char* a1 = cA + (size_t)(t + 1) * kstep;
;             const char* a2 = last ? nA : cA + (size_t)(t + 2) * kstep; const char* b2 = last ? nB : cB + (size_t)(t + 2) * kstep;
;             const char* a3 = a2 + kstep; const char* b3 = b2 + kstep;
;             if (last && has_next) S.a_ready(nxt);
;             if constexpr (SP2) {
;             PG8_LDB(B0, 0, 0); PG8_LDB(B1, 0, 1); PG8_SCHED; PG8_LDA(At, 0, 0); PG8_STAGE(PG8_SA(1, 1), a1 + hstepA, voffA);
;             PG8_WAIT_V(8); PG8_WAIT_L(0); PG8_BAR; PG8_MMA(0, 0, At, B0); PG8_MMA(0, 1, At, B1); PG8_BAR; PG8_SCHED;
;             PG8_LDA(At, 0, 1); PG8_STAGE(PG8_SB(0, 0), b2, voffB); PG8_STAGE(PG8_SB(0, 1), b2 + hstep, voffB); PG8_STAGE(PG8_SA(0, 0), a2, voffA);
;             PG8_WAIT_V(8); PG8_WAIT_L(0); PG8_BAR; PG8_MMA(1, 0, At, B0); PG8_MMA(1, 1, At, B1); PG8_BAR; PG8_SCHED;
.LBB0_782:
	s_add_u32 s26, s24, 0xfffc0080
	s_addc_u32 s27, s25, -1
	s_add_i32 s54, 0, 0x10000
	s_cmp_eq_u32 s53, 28
	s_cselect_b32 s29, s15, s27
	s_cselect_b32 s28, s49, s26
	s_cselect_b32 s27, s13, s52
	s_cselect_b32 s26, s50, s51
	s_add_i32 s56, 0, 0x14000
	v_add_u32_e32 v158, s54, v156
	v_add_u32_e32 v174, s56, v156
	ds_read_b128 v[96:99], v158
	ds_read_b128 v[100:103], v158 offset:1024
	ds_read_b128 v[150:153], v158 offset:2048
	ds_read_b128 v[158:161], v158 offset:3072
	ds_read_b128 v[162:165], v174
	ds_read_b128 v[166:169], v174 offset:1024
	ds_read_b128 v[170:173], v174 offset:2048
	ds_read_b128 v[174:177], v174 offset:3072
	s_add_i32 m0, s38, 0xc000
	ds_read_b128 v[178:181], v157
	ds_read_b128 v[182:185], v157 offset:1024
	ds_read_b128 v[186:189], v157 offset:2048
	ds_read_b128 v[200:203], v157 offset:3072
	ds_read_b128 v[204:207], v157 offset:4096
	ds_read_b128 v[208:211], v157 offset:5120
	ds_read_b128 v[212:215], v157 offset:6144
	global_load_lds_dwordx4 v148, s[24:25]
	s_add_i32 m0, s38, 0xe000
	ds_read_b128 v[216:219], v157 offset:7168
	global_load_lds_dwordx4 v146, s[24:25]
	s_waitcnt vmcnt(8)
	s_waitcnt lgkmcnt(0)
	s_barrier
	s_setprio 1
	v_mfma_f32_16x16x32_bf16 v[132:135], v[96:99], v[178:181], v[132:135]
	v_mfma_f32_16x16x32_bf16 v[128:131], v[150:153], v[178:181], v[128:131]
	v_mfma_f32_16x16x32_bf16 v[124:127], v[96:99], v[186:189], v[124:127]
	v_mfma_f32_16x16x32_bf16 v[120:123], v[150:153], v[186:189], v[120:123]
	v_mfma_f32_16x16x32_bf16 v[116:119], v[96:99], v[204:207], v[116:119]
	v_mfma_f32_16x16x32_bf16 v[112:115], v[150:153], v[204:207], v[112:115]
	v_mfma_f32_16x16x32_bf16 v[108:111], v[96:99], v[212:215], v[108:111]
	v_mfma_f32_16x16x32_bf16 v[104:107], v[150:153], v[212:215], v[104:107]
	v_mfma_f32_16x16x32_bf16 v[132:135], v[100:103], v[182:185], v[132:135]
	v_mfma_f32_16x16x32_bf16 v[128:131], v[158:161], v[182:185], v[128:131]
	v_mfma_f32_16x16x32_bf16 v[124:127], v[100:103], v[200:203], v[124:127]
	v_mfma_f32_16x16x32_bf16 v[120:123], v[158:161], v[200:203], v[120:123]
	v_mfma_f32_16x16x32_bf16 v[116:119], v[100:103], v[208:211], v[116:119]
	v_mfma_f32_16x16x32_bf16 v[112:115], v[158:161], v[208:211], v[112:115]
	v_mfma_f32_16x16x32_bf16 v[108:111], v[100:103], v[216:219], v[108:111]
	v_mfma_f32_16x16x32_bf16 v[104:107], v[158:161], v[216:219], v[104:107]
	s_setprio 0
	s_setprio 1
	v_mfma_f32_16x16x32_bf16 v[60:63], v[162:165], v[178:181], v[60:63]
	v_mfma_f32_16x16x32_bf16 v[56:59], v[170:173], v[178:181], v[56:59]
	v_mfma_f32_16x16x32_bf16 v[52:55], v[162:165], v[186:189], v[52:55]
	v_mfma_f32_16x16x32_bf16 v[48:51], v[170:173], v[186:189], v[48:51]
	v_mfma_f32_16x16x32_bf16 v[44:47], v[162:165], v[204:207], v[44:47]
	v_mfma_f32_16x16x32_bf16 v[40:43], v[170:173], v[204:207], v[40:43]
	v_mfma_f32_16x16x32_bf16 v[36:39], v[162:165], v[212:215], v[36:39]
	v_mfma_f32_16x16x32_bf16 v[32:35], v[170:173], v[212:215], v[32:35]
	v_mfma_f32_16x16x32_bf16 v[60:63], v[166:169], v[182:185], v[60:63]
	v_mfma_f32_16x16x32_bf16 v[56:59], v[174:177], v[182:185], v[56:59]
	v_mfma_f32_16x16x32_bf16 v[52:55], v[166:169], v[200:203], v[52:55]
	v_mfma_f32_16x16x32_bf16 v[48:51], v[174:177], v[200:203], v[48:51]
	v_mfma_f32_16x16x32_bf16 v[44:47], v[166:169], v[208:211], v[44:47]
	v_mfma_f32_16x16x32_bf16 v[40:43], v[174:177], v[208:211], v[40:43]
	v_mfma_f32_16x16x32_bf16 v[36:39], v[166:169], v[216:219], v[36:39]
	v_mfma_f32_16x16x32_bf16 v[32:35], v[174:177], v[216:219], v[32:35]
	s_setprio 0
	s_barrier
	s_add_i32 s54, s54, s35
	s_mov_b64 s[100:101], s[26:27]
	s_mov_b32 m0, s54
	ds_read_b128 v[178:181], v157 offset:16384
	ds_read_b128 v[182:185], v157 offset:17408
	ds_read_b128 v[186:189], v157 offset:18432
	ds_read_b128 v[200:203], v157 offset:19456
	ds_read_b128 v[204:207], v157 offset:20480
	global_load_lds_dwordx4 v190, s[100:101]
	s_add_i32 m0, s54, 0x2000
	s_add_u32 s54, s26, 0x80000
	s_addc_u32 s55, s27, 0
	s_add_i32 s56, s56, s35
	global_load_lds_dwordx4 v136, s[100:101]
	s_mov_b32 m0, s56
	v_lshl_add_u64 v[232:233], s[28:29], 0, v[138:139]
	global_load_lds_dwordx4 v190, s[54:55]
	s_add_i32 m0, s56, 0x2000
	ds_read_b128 v[208:211], v157 offset:21504
	global_load_lds_dwordx4 v136, s[54:55]
	v_lshl_add_u64 v[230:231], s[28:29], 0, v[140:141]
	s_mov_b32 m0, s38
	ds_read_b128 v[212:215], v157 offset:22528
	global_load_lds_dwordx4 v[230:231], off
	s_mov_b32 m0, s40
	ds_read_b128 v[216:219], v157 offset:23552
	global_load_lds_dwordx4 v[232:233], off
	s_waitcnt vmcnt(8)
	s_waitcnt lgkmcnt(0)
	s_barrier
	s_setprio 1
	v_mfma_f32_16x16x32_bf16 v[92:95], v[96:99], v[178:181], v[92:95]
	v_mfma_f32_16x16x32_bf16 v[88:91], v[150:153], v[178:181], v[88:91]
	v_mfma_f32_16x16x32_bf16 v[84:87], v[96:99], v[186:189], v[84:87]
	v_mfma_f32_16x16x32_bf16 v[80:83], v[150:153], v[186:189], v[80:83]
	v_mfma_f32_16x16x32_bf16 v[76:79], v[96:99], v[204:207], v[76:79]
	v_mfma_f32_16x16x32_bf16 v[72:75], v[150:153], v[204:207], v[72:75]
	v_mfma_f32_16x16x32_bf16 v[68:71], v[96:99], v[212:215], v[68:71]
	v_mfma_f32_16x16x32_bf16 v[64:67], v[150:153], v[212:215], v[64:67]
	v_mfma_f32_16x16x32_bf16 v[92:95], v[100:103], v[182:185], v[92:95]
	v_mfma_f32_16x16x32_bf16 v[88:91], v[158:161], v[182:185], v[88:91]
	v_mfma_f32_16x16x32_bf16 v[84:87], v[100:103], v[200:203], v[84:87]
	v_mfma_f32_16x16x32_bf16 v[80:83], v[158:161], v[200:203], v[80:83]
	v_mfma_f32_16x16x32_bf16 v[76:79], v[100:103], v[208:211], v[76:79]
	v_mfma_f32_16x16x32_bf16 v[72:75], v[158:161], v[208:211], v[72:75]
	v_mfma_f32_16x16x32_bf16 v[68:71], v[100:103], v[216:219], v[68:71]
	v_mfma_f32_16x16x32_bf16 v[64:67], v[158:161], v[216:219], v[64:67]
	s_setprio 0
	s_setprio 1
	v_mfma_f32_16x16x32_bf16 v[28:31], v[162:165], v[178:181], v[28:31]
	v_mfma_f32_16x16x32_bf16 v[24:27], v[170:173], v[178:181], v[24:27]
	v_mfma_f32_16x16x32_bf16 v[20:23], v[162:165], v[186:189], v[20:23]
	v_mfma_f32_16x16x32_bf16 v[16:19], v[170:173], v[186:189], v[16:19]
	v_mfma_f32_16x16x32_bf16 v[12:15], v[162:165], v[204:207], v[12:15]
	v_mfma_f32_16x16x32_bf16 v[8:11], v[170:173], v[204:207], v[8:11]
	v_mfma_f32_16x16x32_bf16 v[4:7], v[162:165], v[212:215], v[4:7]
	v_mfma_f32_16x16x32_bf16 v[0:3], v[170:173], v[212:215], v[0:3]
	v_mfma_f32_16x16x32_bf16 v[28:31], v[166:169], v[182:185], v[28:31]
	v_mfma_f32_16x16x32_bf16 v[24:27], v[174:177], v[182:185], v[24:27]
	v_mfma_f32_16x16x32_bf16 v[20:23], v[166:169], v[200:203], v[20:23]
	v_mfma_f32_16x16x32_bf16 v[16:19], v[174:177], v[200:203], v[16:19]
	v_mfma_f32_16x16x32_bf16 v[12:15], v[166:169], v[208:211], v[12:15]
	v_mfma_f32_16x16x32_bf16 v[8:11], v[174:177], v[208:211], v[8:11]
	v_mfma_f32_16x16x32_bf16 v[4:7], v[166:169], v[216:219], v[4:7]
	v_mfma_f32_16x16x32_bf16 v[0:3], v[174:177], v[216:219], v[0:3]
	s_setprio 0
	s_barrier
; #define PG8_STAGE(bufoff, gbase, voff) do { _Pragma("unroll") for (int _i = 0; _i < 2; ++_i) \
;         __builtin_amdgcn_global_load_lds((const unsigned*)((const char*)(gbase) + (voff)[_i]), (PG8_LAS unsigned*)(lds + (bufoff) + ldsw + _i * 8192), 16, 0, 0); } while (0)
; #define PG8_LDA(dst, b, h) do { _Pragma("unroll") for (int m = 0; m < 4; ++m) _Pragma("unroll") for (int k = 0; k < 2; ++k) dst[m][k] = *(const PG8_LAS bf16x8*)(lds + PG8_SA(b, h) + aoff + m * 2048 + k * 1024); } while (0)
; #define PG8_LDB(dst, b, h) do { _Pragma("unroll") for (int n = 0; n < 2; ++n) _Pragma("unroll") for (int k = 0; k < 2; ++k) dst[n][k] = *(const PG8_LAS bf16x8*)(lds + PG8_SB(b, h) + boff + n * 2048 + k * 1024); } while (0)
; #define PG8_MMA(ai, bj, At, Bt) do { __builtin_amdgcn_s_setprio(1); _Pragma("unroll") for (int m = 0; m < 4; ++m) _Pragma("unroll") for (int n = 0; n < 2; ++n) _Pragma("unroll") for (int k = 0; k < 2; ++k) \
;         acc[ai][bj][m][n] = __builtin_amdgcn_mfma_f32_16x16x32_bf16(Bt[n][k], At[m][k], acc[ai][bj][m][n], 0, 0, 0); __builtin_amdgcn_s_setprio(0); } while (0)
; #define PG8_WAIT_V(n) asm volatile("s_waitcnt vmcnt(" #n ")" ::: "memory")
; #define PG8_WAIT_L(n) asm volatile("s_waitcnt lgkmcnt(" #n ")" ::: "memory")
; #define PG8_BAR __builtin_amdgcn_s_barrier()
; #define PG8_SCHED __builtin_amdgcn_sched_barrier(0)
; template <class Epi, class Sched, bool ALIGN_EPI = false, bool SP2 = false>
; __device__ __forceinline__ void gemm_phase(PG8_LAS unsigned char* lds, const Gemm g, const Sched& S, const Epi& E, int tid_in) {
;     ...
;             PG8_LDB(B0, 1, 0); PG8_LDB(B1, 1, 1); PG8_SCHED; PG8_LDA(At, 1, 0); PG8_STAGE(PG8_SA(0, 1), a2 + hstepA, voffA);
;             PG8_WAIT_V(8); PG8_WAIT_L(0); PG8_BAR; PG8_MMA(0, 0, At, B0); PG8_MMA(0, 1, At, B1); PG8_BAR; PG8_SCHED;
;             PG8_LDA(At, 1, 1); PG8_STAGE(PG8_SB(1, 0), b3, voffB); PG8_STAGE(PG8_SB(1, 1), b3 + hstep, voffB); PG8_STAGE(PG8_SA(1, 0), a3, voffA);
;             PG8_WAIT_V(8); PG8_WAIT_L(0); PG8_BAR; PG8_MMA(1, 0, At, B0); PG8_MMA(1, 1, At, B1); PG8_BAR; PG8_SCHED;
	s_add_i32 s54, 0, 0x18000
	s_add_i32 s55, 0, 0x1c000
	v_add_u32_e32 v158, s54, v156
	v_add_u32_e32 v174, s55, v156
	ds_read_b128 v[96:99], v158
	ds_read_b128 v[100:103], v158 offset:1024
	ds_read_b128 v[150:153], v158 offset:2048
	ds_read_b128 v[158:161], v158 offset:3072
	ds_read_b128 v[162:165], v174
	ds_read_b128 v[166:169], v174 offset:1024
	ds_read_b128 v[170:173], v174 offset:2048
	ds_read_b128 v[174:177], v174 offset:3072
	s_add_u32 s28, s28, 0x40000
	s_addc_u32 s29, s29, 0
	s_mov_b32 m0, s41
	ds_read_b128 v[178:181], v157 offset:32768
	ds_read_b128 v[182:185], v157 offset:33792
	ds_read_b128 v[186:189], v157 offset:34816
	ds_read_b128 v[200:203], v157 offset:35840
	ds_read_b128 v[204:207], v157 offset:36864
	ds_read_b128 v[208:211], v157 offset:37888
	ds_read_b128 v[212:215], v157 offset:38912
	global_load_lds_dwordx4 v140, s[28:29]
	s_mov_b32 m0, s42
	ds_read_b128 v[216:219], v157 offset:39936
	global_load_lds_dwordx4 v138, s[28:29]
	s_waitcnt vmcnt(8)
	s_waitcnt lgkmcnt(0)
	s_barrier
	s_setprio 1
	v_mfma_f32_16x16x32_bf16 v[132:135], v[96:99], v[178:181], v[132:135]
	v_mfma_f32_16x16x32_bf16 v[128:131], v[150:153], v[178:181], v[128:131]
	v_mfma_f32_16x16x32_bf16 v[124:127], v[96:99], v[186:189], v[124:127]
	v_mfma_f32_16x16x32_bf16 v[120:123], v[150:153], v[186:189], v[120:123]
	v_mfma_f32_16x16x32_bf16 v[116:119], v[96:99], v[204:207], v[116:119]
	v_mfma_f32_16x16x32_bf16 v[112:115], v[150:153], v[204:207], v[112:115]
	v_mfma_f32_16x16x32_bf16 v[108:111], v[96:99], v[212:215], v[108:111]
	v_mfma_f32_16x16x32_bf16 v[104:107], v[150:153], v[212:215], v[104:107]
	v_mfma_f32_16x16x32_bf16 v[132:135], v[100:103], v[182:185], v[132:135]
	v_mfma_f32_16x16x32_bf16 v[128:131], v[158:161], v[182:185], v[128:131]
	v_mfma_f32_16x16x32_bf16 v[124:127], v[100:103], v[200:203], v[124:127]
	v_mfma_f32_16x16x32_bf16 v[120:123], v[158:161], v[200:203], v[120:123]
	v_mfma_f32_16x16x32_bf16 v[116:119], v[100:103], v[208:211], v[116:119]
	v_mfma_f32_16x16x32_bf16 v[112:115], v[158:161], v[208:211], v[112:115]
	v_mfma_f32_16x16x32_bf16 v[108:111], v[100:103], v[216:219], v[108:111]
	v_mfma_f32_16x16x32_bf16 v[104:107], v[158:161], v[216:219], v[104:107]
	s_setprio 0
	s_setprio 1
	v_mfma_f32_16x16x32_bf16 v[60:63], v[162:165], v[178:181], v[60:63]
	v_mfma_f32_16x16x32_bf16 v[56:59], v[170:173], v[178:181], v[56:59]
	v_mfma_f32_16x16x32_bf16 v[52:55], v[162:165], v[186:189], v[52:55]
	v_mfma_f32_16x16x32_bf16 v[48:51], v[170:173], v[186:189], v[48:51]
	v_mfma_f32_16x16x32_bf16 v[44:47], v[162:165], v[204:207], v[44:47]
	v_mfma_f32_16x16x32_bf16 v[40:43], v[170:173], v[204:207], v[40:43]
	v_mfma_f32_16x16x32_bf16 v[36:39], v[162:165], v[212:215], v[36:39]
	v_mfma_f32_16x16x32_bf16 v[32:35], v[170:173], v[212:215], v[32:35]
	v_mfma_f32_16x16x32_bf16 v[60:63], v[166:169], v[182:185], v[60:63]
	v_mfma_f32_16x16x32_bf16 v[56:59], v[174:177], v[182:185], v[56:59]
	v_mfma_f32_16x16x32_bf16 v[52:55], v[166:169], v[200:203], v[52:55]
	v_mfma_f32_16x16x32_bf16 v[48:51], v[174:177], v[200:203], v[48:51]
	v_mfma_f32_16x16x32_bf16 v[44:47], v[166:169], v[208:211], v[44:47]
	v_mfma_f32_16x16x32_bf16 v[40:43], v[174:177], v[208:211], v[40:43]
	v_mfma_f32_16x16x32_bf16 v[36:39], v[166:169], v[216:219], v[36:39]
	v_mfma_f32_16x16x32_bf16 v[32:35], v[174:177], v[216:219], v[32:35]
	s_setprio 0
	s_barrier
	s_add_i32 s28, s54, s35
	s_mov_b32 m0, s28
	ds_read_b128 v[178:181], v157 offset:49152
	ds_read_b128 v[182:185], v157 offset:50176
	ds_read_b128 v[186:189], v157 offset:51200
	ds_read_b128 v[200:203], v157 offset:52224
	s_add_u32 s100, s100, 0x80
	s_addc_u32 s101, s101, 0
	global_load_lds_dwordx4 v190, s[100:101]
	s_add_i32 m0, s28, 0x2000
	s_add_u32 s26, s26, 0x80080
	s_addc_u32 s27, s27, 0
	s_add_i32 s28, s55, s35
	global_load_lds_dwordx4 v136, s[100:101]
	s_mov_b32 m0, s28
	ds_read_b128 v[204:207], v157 offset:53248
	global_load_lds_dwordx4 v190, s[26:27]
	s_add_i32 m0, s28, 0x2000
	ds_read_b128 v[208:211], v157 offset:54272
	global_load_lds_dwordx4 v136, s[26:27]
	v_lshl_add_u64 v[226:227], v[230:231], 0, s[0:1]
	s_mov_b32 m0, s45
	ds_read_b128 v[212:215], v157 offset:55296
	global_load_lds_dwordx4 v[226:227], off
	v_lshl_add_u64 v[226:227], v[232:233], 0, s[0:1]
	s_mov_b32 m0, s46
	ds_read_b128 v[216:219], v157 offset:56320
	global_load_lds_dwordx4 v[226:227], off
	s_waitcnt vmcnt(8)
	s_waitcnt lgkmcnt(0)
	s_barrier
	s_setprio 1
	v_mfma_f32_16x16x32_bf16 v[92:95], v[96:99], v[178:181], v[92:95]
	v_mfma_f32_16x16x32_bf16 v[88:91], v[150:153], v[178:181], v[88:91]
	v_mfma_f32_16x16x32_bf16 v[84:87], v[96:99], v[186:189], v[84:87]
	v_mfma_f32_16x16x32_bf16 v[80:83], v[150:153], v[186:189], v[80:83]
	v_mfma_f32_16x16x32_bf16 v[76:79], v[96:99], v[204:207], v[76:79]
	v_mfma_f32_16x16x32_bf16 v[72:75], v[150:153], v[204:207], v[72:75]
	v_mfma_f32_16x16x32_bf16 v[68:71], v[96:99], v[212:215], v[68:71]
	v_mfma_f32_16x16x32_bf16 v[64:67], v[150:153], v[212:215], v[64:67]
	v_mfma_f32_16x16x32_bf16 v[92:95], v[100:103], v[182:185], v[92:95]
	v_mfma_f32_16x16x32_bf16 v[88:91], v[158:161], v[182:185], v[88:91]
	v_mfma_f32_16x16x32_bf16 v[84:87], v[100:103], v[200:203], v[84:87]
	v_mfma_f32_16x16x32_bf16 v[80:83], v[158:161], v[200:203], v[80:83]
	v_mfma_f32_16x16x32_bf16 v[76:79], v[100:103], v[208:211], v[76:79]
	v_mfma_f32_16x16x32_bf16 v[72:75], v[158:161], v[208:211], v[72:75]
	v_mfma_f32_16x16x32_bf16 v[68:71], v[100:103], v[216:219], v[68:71]
	v_mfma_f32_16x16x32_bf16 v[64:67], v[158:161], v[216:219], v[64:67]
	s_setprio 0
	s_setprio 1
	v_mfma_f32_16x16x32_bf16 v[28:31], v[162:165], v[178:181], v[28:31]
	v_mfma_f32_16x16x32_bf16 v[24:27], v[170:173], v[178:181], v[24:27]
	v_mfma_f32_16x16x32_bf16 v[20:23], v[162:165], v[186:189], v[20:23]
	v_mfma_f32_16x16x32_bf16 v[16:19], v[170:173], v[186:189], v[16:19]
	v_mfma_f32_16x16x32_bf16 v[12:15], v[162:165], v[204:207], v[12:15]
	v_mfma_f32_16x16x32_bf16 v[8:11], v[170:173], v[204:207], v[8:11]
	v_mfma_f32_16x16x32_bf16 v[4:7], v[162:165], v[212:215], v[4:7]
	v_mfma_f32_16x16x32_bf16 v[0:3], v[170:173], v[212:215], v[0:3]
	v_mfma_f32_16x16x32_bf16 v[28:31], v[166:169], v[182:185], v[28:31]
	v_mfma_f32_16x16x32_bf16 v[24:27], v[174:177], v[182:185], v[24:27]
	v_mfma_f32_16x16x32_bf16 v[20:23], v[166:169], v[200:203], v[20:23]
	v_mfma_f32_16x16x32_bf16 v[16:19], v[174:177], v[200:203], v[16:19]
	v_mfma_f32_16x16x32_bf16 v[12:15], v[166:169], v[208:211], v[12:15]
	v_mfma_f32_16x16x32_bf16 v[8:11], v[174:177], v[208:211], v[8:11]
	v_mfma_f32_16x16x32_bf16 v[4:7], v[166:169], v[216:219], v[4:7]
	v_mfma_f32_16x16x32_bf16 v[0:3], v[174:177], v[216:219], v[0:3]
	s_setprio 0
	s_barrier
	s_add_i32 s53, s53, 2
	s_add_u32 s51, s51, 0x100
	s_addc_u32 s52, s52, 0
	s_add_u32 s24, s24, 0x100
	s_addc_u32 s25, s25, 0
	s_cmp_gt_u32 s53, 29
	s_cbranch_scc0 .LBB0_782
	s_and_b64 vcc, exec, s[8:9]
	s_cbranch_vccz .LBB0_785
	s_barrier

; #define PG8_STAGE(bufoff, gbase, voff) do { _Pragma("unroll") for (int _i = 0; _i < 2; ++_i) \
;         __builtin_amdgcn_global_load_lds((const unsigned*)((const char*)(gbase) + (voff)[_i]), (PG8_LAS unsigned*)(lds + (bufoff) + ldsw + _i * 8192), 16, 0, 0); } while (0)
; #define PG8_LDA(dst, b, h) do { _Pragma("unroll") for (int m = 0; m < 4; ++m) _Pragma("unroll") for (int k = 0; k < 2; ++k) dst[m][k] = *(const PG8_LAS bf16x8*)(lds + PG8_SA(b, h) + aoff + m * 2048 + k * 1024); } while (0)
; #define PG8_LDB(dst, b, h) do { _Pragma("unroll") for (int n = 0; n < 2; ++n) _Pragma("unroll") for (int k = 0; k < 2; ++k) dst[n][k] = *(const PG8_LAS bf16x8*)(lds + PG8_SB(b, h) + boff + n * 2048 + k * 1024); } while (0)
; #define PG8_MMA(ai, bj, At, Bt) do { __builtin_amdgcn_s_setprio(1); _Pragma("unroll") for (int m = 0; m < 4; ++m) _Pragma("unroll") for (int n = 0; n < 2; ++n) _Pragma("unroll") for (int k = 0; k < 2; ++k) \
;         acc[ai][bj][m][n] = __builtin_amdgcn_mfma_f32_16x16x32_bf16(Bt[n][k], At[m][k], acc[ai][bj][m][n], 0, 0, 0); __builtin_amdgcn_s_setprio(0); } while (0)
; #define PG8_WAIT_V(n) asm volatile("s_waitcnt vmcnt(" #n ")" ::: "memory")
; #define PG8_WAIT_L(n) asm volatile("s_waitcnt lgkmcnt(" #n ")" ::: "memory")
; template <class Epi, class Sched, bool ALIGN_EPI = false, bool SP2 = false>
; __device__ __forceinline__ void gemm_phase(PG8_LAS unsigned char* lds, const Gemm g, const Sched& S, const Epi& E, int tid_in) {
;     ...
;             const bool last = (t == nt - 2);
;             const char* a1 = cA + (size_t)(t + 1) * kstep;
;             const char* a2 = last ? nA : cA + (size_t)(t + 2) * kstep; const char* b2 = last ? nB : cB + (size_t)(t + 2) * kstep;
;             const char* a3 = a2 + kstep; const char* b3 = b2 + kstep;
;             if (last && has_next) S.a_ready(nxt);
;             if constexpr (SP2) {
;             PG8_LDB(B0, 0, 0); PG8_LDB(B1, 0, 1); PG8_SCHED; PG8_LDA(At, 0, 0); PG8_STAGE(PG8_SA(1, 1), a1 + hstepA, voffA);
;             PG8_WAIT_V(8); PG8_WAIT_L(0); PG8_BAR; PG8_MMA(0, 0, At, B0); PG8_MMA(0, 1, At, B1); PG8_BAR; PG8_SCHED;
;             PG8_LDA(At, 0, 1); PG8_STAGE(PG8_SB(0, 0), b2, voffB); PG8_STAGE(PG8_SB(0, 1), b2 + hstep, voffB); PG8_STAGE(PG8_SA(0, 0), a2, voffA);
;             PG8_WAIT_V(8); PG8_WAIT_L(0); PG8_BAR; PG8_MMA(1, 0, At, B0); PG8_MMA(1, 1, At, B1); PG8_BAR; PG8_SCHED;
.LBB0_1283:
	s_add_u32 s14, s12, 0xfffc0080
	s_addc_u32 s15, s13, -1
	s_add_i32 s60, 0, 0x10000
	s_cmp_eq_u32 s59, 12
	s_cselect_b32 s27, s19, s15
	s_cselect_b32 s26, s55, s14
	s_cselect_b32 s15, s11, s58
	s_cselect_b32 s14, s56, s57
	s_add_i32 s62, 0, 0x14000
	v_add_u32_e32 v124, s60, v226
	v_add_u32_e32 v140, s62, v226
	ds_read_b128 v[112:115], v124
	ds_read_b128 v[116:119], v124 offset:1024
	ds_read_b128 v[120:123], v124 offset:2048
	ds_read_b128 v[124:127], v124 offset:3072
	ds_read_b128 v[128:131], v140
	ds_read_b128 v[132:135], v140 offset:1024
	ds_read_b128 v[136:139], v140 offset:2048
	ds_read_b128 v[140:143], v140 offset:3072
	s_add_i32 m0, s35, 0xc000
	ds_read_b128 v[144:147], v227
	ds_read_b128 v[148:151], v227 offset:1024
	ds_read_b128 v[152:155], v227 offset:2048
	ds_read_b128 v[156:159], v227 offset:3072
	ds_read_b128 v[176:179], v227 offset:4096
	ds_read_b128 v[180:183], v227 offset:5120
	ds_read_b128 v[208:211], v227 offset:6144
	global_load_lds_dwordx4 v206, s[12:13]
	s_add_i32 m0, s35, 0xe000
	ds_read_b128 v[212:215], v227 offset:7168
	global_load_lds_dwordx4 v204, s[12:13]
	s_waitcnt vmcnt(8)
	s_waitcnt lgkmcnt(0)
	s_barrier
	s_setprio 1
	v_mfma_f32_16x16x32_bf16 v[172:175], v[112:115], v[144:147], v[172:175]
	v_mfma_f32_16x16x32_bf16 v[168:171], v[120:123], v[144:147], v[168:171]
	v_mfma_f32_16x16x32_bf16 v[108:111], v[112:115], v[152:155], v[108:111]
	v_mfma_f32_16x16x32_bf16 v[104:107], v[120:123], v[152:155], v[104:107]
	v_mfma_f32_16x16x32_bf16 v[92:95], v[112:115], v[176:179], v[92:95]
	v_mfma_f32_16x16x32_bf16 v[88:91], v[120:123], v[176:179], v[88:91]
	v_mfma_f32_16x16x32_bf16 v[76:79], v[112:115], v[208:211], v[76:79]
	v_mfma_f32_16x16x32_bf16 v[72:75], v[120:123], v[208:211], v[72:75]
	v_mfma_f32_16x16x32_bf16 v[172:175], v[116:119], v[148:151], v[172:175]
	v_mfma_f32_16x16x32_bf16 v[168:171], v[124:127], v[148:151], v[168:171]
	v_mfma_f32_16x16x32_bf16 v[108:111], v[116:119], v[156:159], v[108:111]
	v_mfma_f32_16x16x32_bf16 v[104:107], v[124:127], v[156:159], v[104:107]
	v_mfma_f32_16x16x32_bf16 v[92:95], v[116:119], v[180:183], v[92:95]
	v_mfma_f32_16x16x32_bf16 v[88:91], v[124:127], v[180:183], v[88:91]
	v_mfma_f32_16x16x32_bf16 v[76:79], v[116:119], v[212:215], v[76:79]
	v_mfma_f32_16x16x32_bf16 v[72:75], v[124:127], v[212:215], v[72:75]
	s_setprio 0
	s_setprio 1
	v_mfma_f32_16x16x32_bf16 v[164:167], v[128:131], v[144:147], v[164:167]
	v_mfma_f32_16x16x32_bf16 v[100:103], v[128:131], v[152:155], v[100:103]
	v_mfma_f32_16x16x32_bf16 v[96:99], v[136:139], v[152:155], v[96:99]
	v_mfma_f32_16x16x32_bf16 v[84:87], v[128:131], v[176:179], v[84:87]
	v_mfma_f32_16x16x32_bf16 v[80:83], v[136:139], v[176:179], v[80:83]
	v_mfma_f32_16x16x32_bf16 v[68:71], v[128:131], v[208:211], v[68:71]
	v_mfma_f32_16x16x32_bf16 v[64:67], v[136:139], v[208:211], v[64:67]
	v_mfma_f32_16x16x32_bf16 v[164:167], v[132:135], v[148:151], v[164:167]
	v_mfma_f32_16x16x32_bf16 v[144:147], v[136:139], v[144:147], v[160:163]
	v_mfma_f32_16x16x32_bf16 v[100:103], v[132:135], v[156:159], v[100:103]
	v_mfma_f32_16x16x32_bf16 v[96:99], v[140:143], v[156:159], v[96:99]
	v_mfma_f32_16x16x32_bf16 v[84:87], v[132:135], v[180:183], v[84:87]
	v_mfma_f32_16x16x32_bf16 v[80:83], v[140:143], v[180:183], v[80:83]
	v_mfma_f32_16x16x32_bf16 v[68:71], v[132:135], v[212:215], v[68:71]
	v_mfma_f32_16x16x32_bf16 v[64:67], v[140:143], v[212:215], v[64:67]
	v_mfma_f32_16x16x32_bf16 v[144:147], v[140:143], v[148:151], v[144:147]
	s_setprio 0
	s_barrier
	s_add_i32 s60, s60, s34
	s_mov_b32 m0, s60
	ds_read_b128 v[148:151], v227 offset:16384
	ds_read_b128 v[152:155], v227 offset:17408
	ds_read_b128 v[156:159], v227 offset:18432
	ds_read_b128 v[160:163], v227 offset:19456
	ds_read_b128 v[176:179], v227 offset:20480
	global_load_lds_dwordx4 v190, s[14:15]
	s_add_i32 m0, s60, 0x2000
	s_add_u32 s60, s14, 0x40000
	s_addc_u32 s61, s15, 0
	s_add_i32 s62, s62, s34
	global_load_lds_dwordx4 v184, s[14:15]
	s_mov_b32 m0, s62
	s_mov_b64 s[100:101], s[26:27]
	global_load_lds_dwordx4 v190, s[60:61]
	s_add_i32 m0, s62, 0x2000
	ds_read_b128 v[180:183], v227 offset:21504
	global_load_lds_dwordx4 v184, s[60:61]
	s_mov_b32 m0, s35
	ds_read_b128 v[208:211], v227 offset:22528
	global_load_lds_dwordx4 v188, s[100:101]
	s_mov_b32 m0, s46
	ds_read_b128 v[212:215], v227 offset:23552
	global_load_lds_dwordx4 v186, s[100:101]
	s_waitcnt vmcnt(8)
	s_waitcnt lgkmcnt(0)
	s_barrier
	s_setprio 1
	v_mfma_f32_16x16x32_bf16 v[60:63], v[112:115], v[148:151], v[60:63]
	v_mfma_f32_16x16x32_bf16 v[56:59], v[120:123], v[148:151], v[56:59]
	v_mfma_f32_16x16x32_bf16 v[44:47], v[112:115], v[156:159], v[44:47]
	v_mfma_f32_16x16x32_bf16 v[40:43], v[120:123], v[156:159], v[40:43]
	v_mfma_f32_16x16x32_bf16 v[28:31], v[112:115], v[176:179], v[28:31]
	v_mfma_f32_16x16x32_bf16 v[24:27], v[120:123], v[176:179], v[24:27]
	v_mfma_f32_16x16x32_bf16 v[12:15], v[112:115], v[208:211], v[12:15]
	v_mfma_f32_16x16x32_bf16 v[8:11], v[120:123], v[208:211], v[8:11]
	v_mfma_f32_16x16x32_bf16 v[60:63], v[116:119], v[152:155], v[60:63]
	v_mfma_f32_16x16x32_bf16 v[56:59], v[124:127], v[152:155], v[56:59]
	v_mfma_f32_16x16x32_bf16 v[44:47], v[116:119], v[160:163], v[44:47]
	v_mfma_f32_16x16x32_bf16 v[40:43], v[124:127], v[160:163], v[40:43]
	v_mfma_f32_16x16x32_bf16 v[28:31], v[116:119], v[180:183], v[28:31]
	v_mfma_f32_16x16x32_bf16 v[24:27], v[124:127], v[180:183], v[24:27]
	v_mfma_f32_16x16x32_bf16 v[12:15], v[116:119], v[212:215], v[12:15]
	v_mfma_f32_16x16x32_bf16 v[8:11], v[124:127], v[212:215], v[8:11]
	s_setprio 0
	s_setprio 1
	v_mfma_f32_16x16x32_bf16 v[52:55], v[128:131], v[148:151], v[52:55]
	v_mfma_f32_16x16x32_bf16 v[48:51], v[136:139], v[148:151], v[48:51]
	v_mfma_f32_16x16x32_bf16 v[36:39], v[128:131], v[156:159], v[36:39]
	v_mfma_f32_16x16x32_bf16 v[32:35], v[136:139], v[156:159], v[32:35]
	v_mfma_f32_16x16x32_bf16 v[20:23], v[128:131], v[176:179], v[20:23]
	v_mfma_f32_16x16x32_bf16 v[16:19], v[136:139], v[176:179], v[16:19]
	v_mfma_f32_16x16x32_bf16 v[4:7], v[128:131], v[208:211], v[4:7]
	v_mfma_f32_16x16x32_bf16 v[0:3], v[136:139], v[208:211], v[0:3]
	v_mfma_f32_16x16x32_bf16 v[52:55], v[132:135], v[152:155], v[52:55]
	v_mfma_f32_16x16x32_bf16 v[48:51], v[140:143], v[152:155], v[48:51]
	v_mfma_f32_16x16x32_bf16 v[36:39], v[132:135], v[160:163], v[36:39]
	v_mfma_f32_16x16x32_bf16 v[32:35], v[140:143], v[160:163], v[32:35]
	v_mfma_f32_16x16x32_bf16 v[20:23], v[132:135], v[180:183], v[20:23]
	v_mfma_f32_16x16x32_bf16 v[16:19], v[140:143], v[180:183], v[16:19]
	v_mfma_f32_16x16x32_bf16 v[4:7], v[132:135], v[212:215], v[4:7]
	v_mfma_f32_16x16x32_bf16 v[0:3], v[140:143], v[212:215], v[0:3]
	s_setprio 0
	s_barrier
; #define PG8_STAGE(bufoff, gbase, voff) do { _Pragma("unroll") for (int _i = 0; _i < 2; ++_i) \
;         __builtin_amdgcn_global_load_lds((const unsigned*)((const char*)(gbase) + (voff)[_i]), (PG8_LAS unsigned*)(lds + (bufoff) + ldsw + _i * 8192), 16, 0, 0); } while (0)
; #define PG8_LDA(dst, b, h) do { _Pragma("unroll") for (int m = 0; m < 4; ++m) _Pragma("unroll") for (int k = 0; k < 2; ++k) dst[m][k] = *(const PG8_LAS bf16x8*)(lds + PG8_SA(b, h) + aoff + m * 2048 + k * 1024); } while (0)
; #define PG8_LDB(dst, b, h) do { _Pragma("unroll") for (int n = 0; n < 2; ++n) _Pragma("unroll") for (int k = 0; k < 2; ++k) dst[n][k] = *(const PG8_LAS bf16x8*)(lds + PG8_SB(b, h) + boff + n * 2048 + k * 1024); } while (0)
; #define PG8_MMA(ai, bj, At, Bt) do { __builtin_amdgcn_s_setprio(1); _Pragma("unroll") for (int m = 0; m < 4; ++m) _Pragma("unroll") for (int n = 0; n < 2; ++n) _Pragma("unroll") for (int k = 0; k < 2; ++k) \
;         acc[ai][bj][m][n] = __builtin_amdgcn_mfma_f32_16x16x32_bf16(Bt[n][k], At[m][k], acc[ai][bj][m][n], 0, 0, 0); __builtin_amdgcn_s_setprio(0); } while (0)
; #define PG8_WAIT_V(n) asm volatile("s_waitcnt vmcnt(" #n ")" ::: "memory")
; #define PG8_WAIT_L(n) asm volatile("s_waitcnt lgkmcnt(" #n ")" ::: "memory")
; #define PG8_BAR __builtin_amdgcn_s_barrier()
; #define PG8_SCHED __builtin_amdgcn_sched_barrier(0)
; template <class Epi, class Sched, bool ALIGN_EPI = false, bool SP2 = false>
; __device__ __forceinline__ void gemm_phase(PG8_LAS unsigned char* lds, const Gemm g, const Sched& S, const Epi& E, int tid_in) {
;     ...
;             PG8_LDB(B0, 1, 0); PG8_LDB(B1, 1, 1); PG8_SCHED; PG8_LDA(At, 1, 0); PG8_STAGE(PG8_SA(0, 1), a2 + hstepA, voffA);
;             PG8_WAIT_V(8); PG8_WAIT_L(0); PG8_BAR; PG8_MMA(0, 0, At, B0); PG8_MMA(0, 1, At, B1); PG8_BAR; PG8_SCHED;
;             PG8_LDA(At, 1, 1); PG8_STAGE(PG8_SB(1, 0), b3, voffB); PG8_STAGE(PG8_SB(1, 1), b3 + hstep, voffB); PG8_STAGE(PG8_SA(1, 0), a3, voffA);
;             PG8_WAIT_V(8); PG8_WAIT_L(0); PG8_BAR; PG8_MMA(1, 0, At, B0); PG8_MMA(1, 1, At, B1); PG8_BAR; PG8_SCHED;
	s_add_i32 s60, 0, 0x18000
	s_add_i32 s61, 0, 0x1c000
	v_add_u32_e32 v124, s60, v226
	v_add_u32_e32 v140, s61, v226
	ds_read_b128 v[112:115], v124
	ds_read_b128 v[116:119], v124 offset:1024
	ds_read_b128 v[120:123], v124 offset:2048
	ds_read_b128 v[124:127], v124 offset:3072
	ds_read_b128 v[128:131], v140
	ds_read_b128 v[132:135], v140 offset:1024
	ds_read_b128 v[136:139], v140 offset:2048
	ds_read_b128 v[140:143], v140 offset:3072
	s_add_u32 s26, s26, 0x40000
	s_addc_u32 s27, s27, 0
	s_mov_b32 m0, s47
	ds_read_b128 v[148:151], v227 offset:32768
	ds_read_b128 v[152:155], v227 offset:33792
	ds_read_b128 v[156:159], v227 offset:34816
	ds_read_b128 v[176:179], v227 offset:35840
	ds_read_b128 v[180:183], v227 offset:36864
	ds_read_b128 v[208:211], v227 offset:37888
	ds_read_b128 v[212:215], v227 offset:38912
	global_load_lds_dwordx4 v188, s[26:27]
	s_mov_b32 m0, s49
	ds_read_b128 v[216:219], v227 offset:39936
	global_load_lds_dwordx4 v186, s[26:27]
	s_waitcnt vmcnt(8)
	s_waitcnt lgkmcnt(0)
	s_barrier
	s_setprio 1
	v_mfma_f32_16x16x32_bf16 v[160:163], v[112:115], v[148:151], v[172:175]
	v_mfma_f32_16x16x32_bf16 v[172:175], v[116:119], v[152:155], v[160:163]
	v_mfma_f32_16x16x32_bf16 v[160:163], v[120:123], v[148:151], v[168:171]
	v_mfma_f32_16x16x32_bf16 v[108:111], v[112:115], v[156:159], v[108:111]
	v_mfma_f32_16x16x32_bf16 v[104:107], v[120:123], v[156:159], v[104:107]
	v_mfma_f32_16x16x32_bf16 v[92:95], v[112:115], v[180:183], v[92:95]
	v_mfma_f32_16x16x32_bf16 v[88:91], v[120:123], v[180:183], v[88:91]
	v_mfma_f32_16x16x32_bf16 v[76:79], v[112:115], v[212:215], v[76:79]
	v_mfma_f32_16x16x32_bf16 v[72:75], v[120:123], v[212:215], v[72:75]
	v_mfma_f32_16x16x32_bf16 v[168:171], v[124:127], v[152:155], v[160:163]
	v_mfma_f32_16x16x32_bf16 v[108:111], v[116:119], v[176:179], v[108:111]
	v_mfma_f32_16x16x32_bf16 v[104:107], v[124:127], v[176:179], v[104:107]
	v_mfma_f32_16x16x32_bf16 v[92:95], v[116:119], v[208:211], v[92:95]
	v_mfma_f32_16x16x32_bf16 v[88:91], v[124:127], v[208:211], v[88:91]
	v_mfma_f32_16x16x32_bf16 v[76:79], v[116:119], v[216:219], v[76:79]
	v_mfma_f32_16x16x32_bf16 v[72:75], v[124:127], v[216:219], v[72:75]
	s_setprio 0
	s_setprio 1
	v_mfma_f32_16x16x32_bf16 v[160:163], v[128:131], v[148:151], v[164:167]
	v_mfma_f32_16x16x32_bf16 v[144:147], v[136:139], v[148:151], v[144:147]
	v_mfma_f32_16x16x32_bf16 v[100:103], v[128:131], v[156:159], v[100:103]
	v_mfma_f32_16x16x32_bf16 v[96:99], v[136:139], v[156:159], v[96:99]
	v_mfma_f32_16x16x32_bf16 v[84:87], v[128:131], v[180:183], v[84:87]
	v_mfma_f32_16x16x32_bf16 v[80:83], v[136:139], v[180:183], v[80:83]
	v_mfma_f32_16x16x32_bf16 v[68:71], v[128:131], v[212:215], v[68:71]
	v_mfma_f32_16x16x32_bf16 v[64:67], v[136:139], v[212:215], v[64:67]
	v_mfma_f32_16x16x32_bf16 v[164:167], v[132:135], v[152:155], v[160:163]
	v_mfma_f32_16x16x32_bf16 v[160:163], v[140:143], v[152:155], v[144:147]
	v_mfma_f32_16x16x32_bf16 v[100:103], v[132:135], v[176:179], v[100:103]
	v_mfma_f32_16x16x32_bf16 v[96:99], v[140:143], v[176:179], v[96:99]
	v_mfma_f32_16x16x32_bf16 v[84:87], v[132:135], v[208:211], v[84:87]
	v_mfma_f32_16x16x32_bf16 v[80:83], v[140:143], v[208:211], v[80:83]
	v_mfma_f32_16x16x32_bf16 v[68:71], v[132:135], v[216:219], v[68:71]
	v_mfma_f32_16x16x32_bf16 v[64:67], v[140:143], v[216:219], v[64:67]
	s_setprio 0
	s_barrier
	s_add_i32 s26, s60, s34
	s_mov_b32 m0, s26
	ds_read_b128 v[144:147], v227 offset:49152
	ds_read_b128 v[148:151], v227 offset:50176
	ds_read_b128 v[152:155], v227 offset:51200
	ds_read_b128 v[156:159], v227 offset:52224
	s_add_u32 s14, s14, 0x80
	s_addc_u32 s15, s15, 0
	global_load_lds_dwordx4 v190, s[14:15]
	s_add_i32 m0, s26, 0x2000
	ds_read_b128 v[176:179], v227 offset:53248
	global_load_lds_dwordx4 v184, s[14:15]
	s_add_u32 s14, s14, 0x40000
	s_addc_u32 s15, s15, 0
	s_add_i32 s26, s61, s34
	s_mov_b32 m0, s26
	ds_read_b128 v[180:183], v227 offset:54272
	global_load_lds_dwordx4 v190, s[14:15]
	s_add_i32 m0, s26, 0x2000
	ds_read_b128 v[208:211], v227 offset:55296
	global_load_lds_dwordx4 v184, s[14:15]
	s_mov_b32 m0, s52
	s_nop 0
	s_add_u32 s100, s100, 0x80
	s_addc_u32 s101, s101, 0
	global_load_lds_dwordx4 v188, s[100:101]
	s_mov_b32 m0, s53
	ds_read_b128 v[212:215], v227 offset:56320
	global_load_lds_dwordx4 v186, s[100:101]
	s_waitcnt vmcnt(8)
	s_waitcnt lgkmcnt(0)
	s_barrier
	s_setprio 1
	v_mfma_f32_16x16x32_bf16 v[60:63], v[112:115], v[144:147], v[60:63]
	v_mfma_f32_16x16x32_bf16 v[56:59], v[120:123], v[144:147], v[56:59]
	v_mfma_f32_16x16x32_bf16 v[44:47], v[112:115], v[152:155], v[44:47]
	v_mfma_f32_16x16x32_bf16 v[40:43], v[120:123], v[152:155], v[40:43]
	v_mfma_f32_16x16x32_bf16 v[28:31], v[112:115], v[176:179], v[28:31]
	v_mfma_f32_16x16x32_bf16 v[24:27], v[120:123], v[176:179], v[24:27]
	v_mfma_f32_16x16x32_bf16 v[12:15], v[112:115], v[208:211], v[12:15]
	v_mfma_f32_16x16x32_bf16 v[8:11], v[120:123], v[208:211], v[8:11]
	v_mfma_f32_16x16x32_bf16 v[60:63], v[116:119], v[148:151], v[60:63]
	v_mfma_f32_16x16x32_bf16 v[56:59], v[124:127], v[148:151], v[56:59]
	v_mfma_f32_16x16x32_bf16 v[44:47], v[116:119], v[156:159], v[44:47]
	v_mfma_f32_16x16x32_bf16 v[40:43], v[124:127], v[156:159], v[40:43]
	v_mfma_f32_16x16x32_bf16 v[28:31], v[116:119], v[180:183], v[28:31]
	v_mfma_f32_16x16x32_bf16 v[24:27], v[124:127], v[180:183], v[24:27]
	v_mfma_f32_16x16x32_bf16 v[12:15], v[116:119], v[212:215], v[12:15]
	v_mfma_f32_16x16x32_bf16 v[8:11], v[124:127], v[212:215], v[8:11]
	s_setprio 0
	s_setprio 1
	v_mfma_f32_16x16x32_bf16 v[52:55], v[128:131], v[144:147], v[52:55]
	v_mfma_f32_16x16x32_bf16 v[48:51], v[136:139], v[144:147], v[48:51]
	v_mfma_f32_16x16x32_bf16 v[36:39], v[128:131], v[152:155], v[36:39]
	v_mfma_f32_16x16x32_bf16 v[32:35], v[136:139], v[152:155], v[32:35]
	v_mfma_f32_16x16x32_bf16 v[20:23], v[128:131], v[176:179], v[20:23]
	v_mfma_f32_16x16x32_bf16 v[16:19], v[136:139], v[176:179], v[16:19]
	v_mfma_f32_16x16x32_bf16 v[4:7], v[128:131], v[208:211], v[4:7]
	v_mfma_f32_16x16x32_bf16 v[0:3], v[136:139], v[208:211], v[0:3]
	v_mfma_f32_16x16x32_bf16 v[52:55], v[132:135], v[148:151], v[52:55]
	v_mfma_f32_16x16x32_bf16 v[48:51], v[140:143], v[148:151], v[48:51]
	v_mfma_f32_16x16x32_bf16 v[36:39], v[132:135], v[156:159], v[36:39]
	v_mfma_f32_16x16x32_bf16 v[32:35], v[140:143], v[156:159], v[32:35]
	v_mfma_f32_16x16x32_bf16 v[20:23], v[132:135], v[180:183], v[20:23]
	v_mfma_f32_16x16x32_bf16 v[16:19], v[140:143], v[180:183], v[16:19]
	v_mfma_f32_16x16x32_bf16 v[4:7], v[132:135], v[212:215], v[4:7]
	v_mfma_f32_16x16x32_bf16 v[0:3], v[140:143], v[212:215], v[0:3]
	s_setprio 0
	s_barrier
	s_add_i32 s59, s59, 2
	s_add_u32 s57, s57, 0x100
	s_addc_u32 s58, s58, 0
	s_add_u32 s12, s12, 0x100
	s_addc_u32 s13, s13, 0
	s_cmp_gt_u32 s59, 13
	s_cbranch_scc0 .LBB0_1283
	s_and_b64 vcc, exec, s[8:9]
	s_cbranch_vccz .LBB0_1286
	s_barrier

; #define PG8_STAGE(bufoff, gbase, voff) do { _Pragma("unroll") for (int _i = 0; _i < 2; ++_i) \
;         __builtin_amdgcn_global_load_lds((const unsigned*)((const char*)(gbase) + (voff)[_i]), (PG8_LAS unsigned*)(lds + (bufoff) + ldsw + _i * 8192), 16, 0, 0); } while (0)
; #define PG8_LDA(dst, b, h) do { _Pragma("unroll") for (int m = 0; m < 4; ++m) _Pragma("unroll") for (int k = 0; k < 2; ++k) dst[m][k] = *(const PG8_LAS bf16x8*)(lds + PG8_SA(b, h) + aoff + m * 2048 + k * 1024); } while (0)
; #define PG8_LDB(dst, b, h) do { _Pragma("unroll") for (int n = 0; n < 2; ++n) _Pragma("unroll") for (int k = 0; k < 2; ++k) dst[n][k] = *(const PG8_LAS bf16x8*)(lds + PG8_SB(b, h) + boff + n * 2048 + k * 1024); } while (0)
; #define PG8_MMA(ai, bj, At, Bt) do { __builtin_amdgcn_s_setprio(1); _Pragma("unroll") for (int m = 0; m < 4; ++m) _Pragma("unroll") for (int n = 0; n < 2; ++n) _Pragma("unroll") for (int k = 0; k < 2; ++k) \
;         acc[ai][bj][m][n] = __builtin_amdgcn_mfma_f32_16x16x32_bf16(Bt[n][k], At[m][k], acc[ai][bj][m][n], 0, 0, 0); __builtin_amdgcn_s_setprio(0); } while (0)
; #define PG8_WAIT_V(n) asm volatile("s_waitcnt vmcnt(" #n ")" ::: "memory")
; #define PG8_WAIT_L(n) asm volatile("s_waitcnt lgkmcnt(" #n ")" ::: "memory")
; template <class Epi, class Sched, bool ALIGN_EPI = false, bool SP2 = false>
; __device__ __forceinline__ void gemm_phase(PG8_LAS unsigned char* lds, const Gemm g, const Sched& S, const Epi& E, int tid_in) {
;     ...
;             const bool last = (t == nt - 2);
;             const char* a1 = cA + (size_t)(t + 1) * kstep;
;             const char* a2 = last ? nA : cA + (size_t)(t + 2) * kstep; const char* b2 = last ? nB : cB + (size_t)(t + 2) * kstep;
;             const char* a3 = a2 + kstep; const char* b3 = b2 + kstep;
;             if (last && has_next) S.a_ready(nxt);
;             if constexpr (SP2) {
;             PG8_LDB(B0, 0, 0); PG8_LDB(B1, 0, 1); PG8_SCHED; PG8_LDA(At, 0, 0); PG8_STAGE(PG8_SA(1, 1), a1 + hstepA, voffA);
;             PG8_WAIT_V(8); PG8_WAIT_L(0); PG8_BAR; PG8_MMA(0, 0, At, B0); PG8_MMA(0, 1, At, B1); PG8_BAR; PG8_SCHED;
;             PG8_LDA(At, 0, 1); PG8_STAGE(PG8_SB(0, 0), b2, voffB); PG8_STAGE(PG8_SB(0, 1), b2 + hstep, voffB); PG8_STAGE(PG8_SA(0, 0), a2, voffA);
;             PG8_WAIT_V(8); PG8_WAIT_L(0); PG8_BAR; PG8_MMA(1, 0, At, B0); PG8_MMA(1, 1, At, B1); PG8_BAR; PG8_SCHED;
.LBB0_1385:
	s_add_u32 s12, s2, 0xfffc0080
	s_addc_u32 s13, s3, -1
	s_add_i32 s58, 0, 0x10000
	s_cmp_eq_u32 s57, 12
	s_cselect_b32 s15, s21, s13
	s_cselect_b32 s14, s53, s12
	v_add_u32_e32 v140, s58, v145
	s_cselect_b32 s13, s19, s56
	s_cselect_b32 s12, s54, s55
	s_add_i32 s60, 0, 0x14000
	ds_read_b128 v[148:151], v140
	ds_read_b128 v[152:155], v140 offset:1024
	ds_read_b128 v[156:159], v140 offset:2048
	ds_read_b128 v[160:163], v140 offset:3072
	v_add_u32_e32 v140, s60, v145
	ds_read_b128 v[164:167], v140
	ds_read_b128 v[168:171], v140 offset:1024
	ds_read_b128 v[172:175], v140 offset:2048
	ds_read_b128 v[176:179], v140 offset:3072
	s_add_i32 m0, s45, 0xc000
	ds_read_b128 v[180:183], v146
	ds_read_b128 v[184:187], v146 offset:1024
	ds_read_b128 v[200:203], v146 offset:2048
	ds_read_b128 v[204:207], v146 offset:3072
	ds_read_b128 v[208:211], v146 offset:4096
	ds_read_b128 v[212:215], v146 offset:5120
	ds_read_b128 v[216:219], v146 offset:6144
	global_load_lds_dwordx4 v138, s[2:3]
	s_add_i32 m0, s45, 0xe000
	ds_read_b128 v[226:229], v146 offset:7168
	global_load_lds_dwordx4 v136, s[2:3]
	s_waitcnt vmcnt(8)
	s_waitcnt lgkmcnt(0)
	s_barrier
	s_setprio 1
	v_mfma_f32_16x16x32_bf16 v[124:127], v[148:151], v[180:183], v[124:127]
	v_mfma_f32_16x16x32_bf16 v[116:119], v[156:159], v[180:183], v[116:119]
	v_mfma_f32_16x16x32_bf16 v[108:111], v[148:151], v[200:203], v[108:111]
	v_mfma_f32_16x16x32_bf16 v[100:103], v[156:159], v[200:203], v[100:103]
	v_mfma_f32_16x16x32_bf16 v[92:95], v[148:151], v[208:211], v[92:95]
	v_mfma_f32_16x16x32_bf16 v[84:87], v[156:159], v[208:211], v[84:87]
	v_mfma_f32_16x16x32_bf16 v[76:79], v[148:151], v[216:219], v[76:79]
	v_mfma_f32_16x16x32_bf16 v[68:71], v[156:159], v[216:219], v[68:71]
	v_mfma_f32_16x16x32_bf16 v[124:127], v[152:155], v[184:187], v[124:127]
	v_mfma_f32_16x16x32_bf16 v[116:119], v[160:163], v[184:187], v[116:119]
	v_mfma_f32_16x16x32_bf16 v[108:111], v[152:155], v[204:207], v[108:111]
	v_mfma_f32_16x16x32_bf16 v[100:103], v[160:163], v[204:207], v[100:103]
	v_mfma_f32_16x16x32_bf16 v[92:95], v[152:155], v[212:215], v[92:95]
	v_mfma_f32_16x16x32_bf16 v[84:87], v[160:163], v[212:215], v[84:87]
	v_mfma_f32_16x16x32_bf16 v[76:79], v[152:155], v[226:229], v[76:79]
	v_mfma_f32_16x16x32_bf16 v[68:71], v[160:163], v[226:229], v[68:71]
	s_setprio 0
	s_setprio 1
	v_mfma_f32_16x16x32_bf16 v[120:123], v[164:167], v[180:183], v[120:123]
	v_mfma_f32_16x16x32_bf16 v[112:115], v[172:175], v[180:183], v[112:115]
	v_mfma_f32_16x16x32_bf16 v[104:107], v[164:167], v[200:203], v[104:107]
	v_mfma_f32_16x16x32_bf16 v[96:99], v[172:175], v[200:203], v[96:99]
	v_mfma_f32_16x16x32_bf16 v[88:91], v[164:167], v[208:211], v[88:91]
	v_mfma_f32_16x16x32_bf16 v[80:83], v[172:175], v[208:211], v[80:83]
	v_mfma_f32_16x16x32_bf16 v[72:75], v[164:167], v[216:219], v[72:75]
	v_mfma_f32_16x16x32_bf16 v[64:67], v[172:175], v[216:219], v[64:67]
	v_mfma_f32_16x16x32_bf16 v[120:123], v[168:171], v[184:187], v[120:123]
	v_mfma_f32_16x16x32_bf16 v[112:115], v[176:179], v[184:187], v[112:115]
	v_mfma_f32_16x16x32_bf16 v[104:107], v[168:171], v[204:207], v[104:107]
	v_mfma_f32_16x16x32_bf16 v[96:99], v[176:179], v[204:207], v[96:99]
	v_mfma_f32_16x16x32_bf16 v[88:91], v[168:171], v[212:215], v[88:91]
	v_mfma_f32_16x16x32_bf16 v[80:83], v[176:179], v[212:215], v[80:83]
	v_mfma_f32_16x16x32_bf16 v[72:75], v[168:171], v[226:229], v[72:75]
	v_mfma_f32_16x16x32_bf16 v[64:67], v[176:179], v[226:229], v[64:67]
	s_setprio 0
	s_barrier
	s_add_i32 s58, s58, s44
	s_mov_b32 m0, s58
	ds_read_b128 v[180:183], v146 offset:16384
	ds_read_b128 v[184:187], v146 offset:17408
	ds_read_b128 v[200:203], v146 offset:18432
	ds_read_b128 v[204:207], v146 offset:19456
	ds_read_b128 v[208:211], v146 offset:20480
	global_load_lds_dwordx4 v132, s[12:13]
	s_add_i32 m0, s58, 0x2000
	s_add_u32 s58, s12, 0x40000
	s_addc_u32 s59, s13, 0
	s_add_i32 s60, s60, s44
	global_load_lds_dwordx4 v128, s[12:13]
	s_mov_b32 m0, s60
	s_mov_b64 s[100:101], s[14:15]
	global_load_lds_dwordx4 v132, s[58:59]
	s_add_i32 m0, s60, 0x2000
	ds_read_b128 v[212:215], v146 offset:21504
	global_load_lds_dwordx4 v128, s[58:59]
	s_mov_b32 m0, s45
	ds_read_b128 v[216:219], v146 offset:22528
	global_load_lds_dwordx4 v134, s[100:101]
	s_mov_b32 m0, s46
	ds_read_b128 v[226:229], v146 offset:23552
	global_load_lds_dwordx4 v130, s[100:101]
	s_waitcnt vmcnt(8)
	s_waitcnt lgkmcnt(0)
	s_barrier
	s_setprio 1
	v_mfma_f32_16x16x32_bf16 v[60:63], v[148:151], v[180:183], v[60:63]
	v_mfma_f32_16x16x32_bf16 v[52:55], v[156:159], v[180:183], v[52:55]
	v_mfma_f32_16x16x32_bf16 v[44:47], v[148:151], v[200:203], v[44:47]
	v_mfma_f32_16x16x32_bf16 v[36:39], v[156:159], v[200:203], v[36:39]
	v_mfma_f32_16x16x32_bf16 v[28:31], v[148:151], v[208:211], v[28:31]
	v_mfma_f32_16x16x32_bf16 v[20:23], v[156:159], v[208:211], v[20:23]
	v_mfma_f32_16x16x32_bf16 v[12:15], v[148:151], v[216:219], v[12:15]
	v_mfma_f32_16x16x32_bf16 v[4:7], v[156:159], v[216:219], v[4:7]
	v_mfma_f32_16x16x32_bf16 v[60:63], v[152:155], v[184:187], v[60:63]
	v_mfma_f32_16x16x32_bf16 v[52:55], v[160:163], v[184:187], v[52:55]
	v_mfma_f32_16x16x32_bf16 v[44:47], v[152:155], v[204:207], v[44:47]
	v_mfma_f32_16x16x32_bf16 v[36:39], v[160:163], v[204:207], v[36:39]
	v_mfma_f32_16x16x32_bf16 v[28:31], v[152:155], v[212:215], v[28:31]
	v_mfma_f32_16x16x32_bf16 v[20:23], v[160:163], v[212:215], v[20:23]
	v_mfma_f32_16x16x32_bf16 v[12:15], v[152:155], v[226:229], v[12:15]
	v_mfma_f32_16x16x32_bf16 v[4:7], v[160:163], v[226:229], v[4:7]
	s_setprio 0
	s_setprio 1
	v_mfma_f32_16x16x32_bf16 v[56:59], v[164:167], v[180:183], v[56:59]
	v_mfma_f32_16x16x32_bf16 v[48:51], v[172:175], v[180:183], v[48:51]
	v_mfma_f32_16x16x32_bf16 v[40:43], v[164:167], v[200:203], v[40:43]
	v_mfma_f32_16x16x32_bf16 v[32:35], v[172:175], v[200:203], v[32:35]
	v_mfma_f32_16x16x32_bf16 v[24:27], v[164:167], v[208:211], v[24:27]
	v_mfma_f32_16x16x32_bf16 v[16:19], v[172:175], v[208:211], v[16:19]
	v_mfma_f32_16x16x32_bf16 v[8:11], v[164:167], v[216:219], v[8:11]
	v_mfma_f32_16x16x32_bf16 v[0:3], v[172:175], v[216:219], v[0:3]
	v_mfma_f32_16x16x32_bf16 v[56:59], v[168:171], v[184:187], v[56:59]
	v_mfma_f32_16x16x32_bf16 v[48:51], v[176:179], v[184:187], v[48:51]
	v_mfma_f32_16x16x32_bf16 v[40:43], v[168:171], v[204:207], v[40:43]
	v_mfma_f32_16x16x32_bf16 v[32:35], v[176:179], v[204:207], v[32:35]
	v_mfma_f32_16x16x32_bf16 v[24:27], v[168:171], v[212:215], v[24:27]
	v_mfma_f32_16x16x32_bf16 v[16:19], v[176:179], v[212:215], v[16:19]
	v_mfma_f32_16x16x32_bf16 v[8:11], v[168:171], v[226:229], v[8:11]
	v_mfma_f32_16x16x32_bf16 v[0:3], v[176:179], v[226:229], v[0:3]
	s_setprio 0
	s_barrier
; #define PG8_STAGE(bufoff, gbase, voff) do { _Pragma("unroll") for (int _i = 0; _i < 2; ++_i) \
;         __builtin_amdgcn_global_load_lds((const unsigned*)((const char*)(gbase) + (voff)[_i]), (PG8_LAS unsigned*)(lds + (bufoff) + ldsw + _i * 8192), 16, 0, 0); } while (0)
; #define PG8_LDA(dst, b, h) do { _Pragma("unroll") for (int m = 0; m < 4; ++m) _Pragma("unroll") for (int k = 0; k < 2; ++k) dst[m][k] = *(const PG8_LAS bf16x8*)(lds + PG8_SA(b, h) + aoff + m * 2048 + k * 1024); } while (0)
; #define PG8_LDB(dst, b, h) do { _Pragma("unroll") for (int n = 0; n < 2; ++n) _Pragma("unroll") for (int k = 0; k < 2; ++k) dst[n][k] = *(const PG8_LAS bf16x8*)(lds + PG8_SB(b, h) + boff + n * 2048 + k * 1024); } while (0)
; #define PG8_MMA(ai, bj, At, Bt) do { __builtin_amdgcn_s_setprio(1); _Pragma("unroll") for (int m = 0; m < 4; ++m) _Pragma("unroll") for (int n = 0; n < 2; ++n) _Pragma("unroll") for (int k = 0; k < 2; ++k) \
;         acc[ai][bj][m][n] = __builtin_amdgcn_mfma_f32_16x16x32_bf16(Bt[n][k], At[m][k], acc[ai][bj][m][n], 0, 0, 0); __builtin_amdgcn_s_setprio(0); } while (0)
; #define PG8_WAIT_V(n) asm volatile("s_waitcnt vmcnt(" #n ")" ::: "memory")
; #define PG8_WAIT_L(n) asm volatile("s_waitcnt lgkmcnt(" #n ")" ::: "memory")
; #define PG8_BAR __builtin_amdgcn_s_barrier()
; #define PG8_SCHED __builtin_amdgcn_sched_barrier(0)
; template <class Epi, class Sched, bool ALIGN_EPI = false, bool SP2 = false>
; __device__ __forceinline__ void gemm_phase(PG8_LAS unsigned char* lds, const Gemm g, const Sched& S, const Epi& E, int tid_in) {
;     ...
;             PG8_LDB(B0, 1, 0); PG8_LDB(B1, 1, 1); PG8_SCHED; PG8_LDA(At, 1, 0); PG8_STAGE(PG8_SA(0, 1), a2 + hstepA, voffA);
;             PG8_WAIT_V(8); PG8_WAIT_L(0); PG8_BAR; PG8_MMA(0, 0, At, B0); PG8_MMA(0, 1, At, B1); PG8_BAR; PG8_SCHED;
;             PG8_LDA(At, 1, 1); PG8_STAGE(PG8_SB(1, 0), b3, voffB); PG8_STAGE(PG8_SB(1, 1), b3 + hstep, voffB); PG8_STAGE(PG8_SA(1, 0), a3, voffA);
;             PG8_WAIT_V(8); PG8_WAIT_L(0); PG8_BAR; PG8_MMA(1, 0, At, B0); PG8_MMA(1, 1, At, B1); PG8_BAR; PG8_SCHED;
	s_add_i32 s58, 0, 0x18000
	v_add_u32_e32 v142, s58, v145
	s_add_i32 s59, 0, 0x1c000
	ds_read_b128 v[148:151], v142
	ds_read_b128 v[152:155], v142 offset:1024
	ds_read_b128 v[156:159], v142 offset:2048
	ds_read_b128 v[160:163], v142 offset:3072
	v_add_u32_e32 v142, s59, v145
	ds_read_b128 v[164:167], v142
	ds_read_b128 v[168:171], v142 offset:1024
	ds_read_b128 v[172:175], v142 offset:2048
	ds_read_b128 v[176:179], v142 offset:3072
	s_add_u32 s14, s14, 0x40000
	s_addc_u32 s15, s15, 0
	s_mov_b32 m0, s47
	ds_read_b128 v[180:183], v146 offset:32768
	ds_read_b128 v[184:187], v146 offset:33792
	ds_read_b128 v[200:203], v146 offset:34816
	ds_read_b128 v[204:207], v146 offset:35840
	ds_read_b128 v[208:211], v146 offset:36864
	ds_read_b128 v[212:215], v146 offset:37888
	ds_read_b128 v[216:219], v146 offset:38912
	global_load_lds_dwordx4 v134, s[14:15]
	s_mov_b32 m0, s49
	ds_read_b128 v[226:229], v146 offset:39936
	global_load_lds_dwordx4 v130, s[14:15]
	s_waitcnt vmcnt(8)
	s_waitcnt lgkmcnt(0)
	s_barrier
	s_setprio 1
	v_mfma_f32_16x16x32_bf16 v[124:127], v[148:151], v[180:183], v[124:127]
	v_mfma_f32_16x16x32_bf16 v[116:119], v[156:159], v[180:183], v[116:119]
	v_mfma_f32_16x16x32_bf16 v[108:111], v[148:151], v[200:203], v[108:111]
	v_mfma_f32_16x16x32_bf16 v[100:103], v[156:159], v[200:203], v[100:103]
	v_mfma_f32_16x16x32_bf16 v[92:95], v[148:151], v[208:211], v[92:95]
	v_mfma_f32_16x16x32_bf16 v[84:87], v[156:159], v[208:211], v[84:87]
	v_mfma_f32_16x16x32_bf16 v[76:79], v[148:151], v[216:219], v[76:79]
	v_mfma_f32_16x16x32_bf16 v[68:71], v[156:159], v[216:219], v[68:71]
	v_mfma_f32_16x16x32_bf16 v[124:127], v[152:155], v[184:187], v[124:127]
	v_mfma_f32_16x16x32_bf16 v[116:119], v[160:163], v[184:187], v[116:119]
	v_mfma_f32_16x16x32_bf16 v[108:111], v[152:155], v[204:207], v[108:111]
	v_mfma_f32_16x16x32_bf16 v[100:103], v[160:163], v[204:207], v[100:103]
	v_mfma_f32_16x16x32_bf16 v[92:95], v[152:155], v[212:215], v[92:95]
	v_mfma_f32_16x16x32_bf16 v[84:87], v[160:163], v[212:215], v[84:87]
	v_mfma_f32_16x16x32_bf16 v[76:79], v[152:155], v[226:229], v[76:79]
	v_mfma_f32_16x16x32_bf16 v[68:71], v[160:163], v[226:229], v[68:71]
	s_setprio 0
	s_setprio 1
	v_mfma_f32_16x16x32_bf16 v[120:123], v[164:167], v[180:183], v[120:123]
	v_mfma_f32_16x16x32_bf16 v[112:115], v[172:175], v[180:183], v[112:115]
	v_mfma_f32_16x16x32_bf16 v[104:107], v[164:167], v[200:203], v[104:107]
	v_mfma_f32_16x16x32_bf16 v[96:99], v[172:175], v[200:203], v[96:99]
	v_mfma_f32_16x16x32_bf16 v[88:91], v[164:167], v[208:211], v[88:91]
	v_mfma_f32_16x16x32_bf16 v[80:83], v[172:175], v[208:211], v[80:83]
	v_mfma_f32_16x16x32_bf16 v[72:75], v[164:167], v[216:219], v[72:75]
	v_mfma_f32_16x16x32_bf16 v[64:67], v[172:175], v[216:219], v[64:67]
	v_mfma_f32_16x16x32_bf16 v[120:123], v[168:171], v[184:187], v[120:123]
	v_mfma_f32_16x16x32_bf16 v[112:115], v[176:179], v[184:187], v[112:115]
	v_mfma_f32_16x16x32_bf16 v[104:107], v[168:171], v[204:207], v[104:107]
	v_mfma_f32_16x16x32_bf16 v[96:99], v[176:179], v[204:207], v[96:99]
	v_mfma_f32_16x16x32_bf16 v[88:91], v[168:171], v[212:215], v[88:91]
	v_mfma_f32_16x16x32_bf16 v[80:83], v[176:179], v[212:215], v[80:83]
	v_mfma_f32_16x16x32_bf16 v[72:75], v[168:171], v[226:229], v[72:75]
	v_mfma_f32_16x16x32_bf16 v[64:67], v[176:179], v[226:229], v[64:67]
	s_setprio 0
	s_barrier
	s_add_i32 s14, s58, s44
	s_mov_b32 m0, s14
	ds_read_b128 v[180:183], v146 offset:49152
	ds_read_b128 v[184:187], v146 offset:50176
	ds_read_b128 v[200:203], v146 offset:51200
	ds_read_b128 v[204:207], v146 offset:52224
	s_add_u32 s12, s12, 0x80
	s_addc_u32 s13, s13, 0
	global_load_lds_dwordx4 v132, s[12:13]
	s_add_i32 m0, s14, 0x2000
	ds_read_b128 v[208:211], v146 offset:53248
	global_load_lds_dwordx4 v128, s[12:13]
	s_add_u32 s12, s12, 0x40000
	s_addc_u32 s13, s13, 0
	s_add_i32 s14, s59, s44
	s_mov_b32 m0, s14
	ds_read_b128 v[212:215], v146 offset:54272
	global_load_lds_dwordx4 v132, s[12:13]
	s_add_i32 m0, s14, 0x2000
	ds_read_b128 v[216:219], v146 offset:55296
	global_load_lds_dwordx4 v128, s[12:13]
	s_mov_b32 m0, s50
	s_nop 0
	s_add_u32 s100, s100, 0x80
	s_addc_u32 s101, s101, 0
	global_load_lds_dwordx4 v134, s[100:101]
	s_mov_b32 m0, s51
	ds_read_b128 v[226:229], v146 offset:56320
	global_load_lds_dwordx4 v130, s[100:101]
	s_waitcnt vmcnt(8)
	s_waitcnt lgkmcnt(0)
	s_barrier
	s_setprio 1
	v_mfma_f32_16x16x32_bf16 v[60:63], v[148:151], v[180:183], v[60:63]
	v_mfma_f32_16x16x32_bf16 v[52:55], v[156:159], v[180:183], v[52:55]
	v_mfma_f32_16x16x32_bf16 v[44:47], v[148:151], v[200:203], v[44:47]
	v_mfma_f32_16x16x32_bf16 v[36:39], v[156:159], v[200:203], v[36:39]
	v_mfma_f32_16x16x32_bf16 v[28:31], v[148:151], v[208:211], v[28:31]
	v_mfma_f32_16x16x32_bf16 v[20:23], v[156:159], v[208:211], v[20:23]
	v_mfma_f32_16x16x32_bf16 v[12:15], v[148:151], v[216:219], v[12:15]
	v_mfma_f32_16x16x32_bf16 v[4:7], v[156:159], v[216:219], v[4:7]
	v_mfma_f32_16x16x32_bf16 v[60:63], v[152:155], v[184:187], v[60:63]
	v_mfma_f32_16x16x32_bf16 v[52:55], v[160:163], v[184:187], v[52:55]
	v_mfma_f32_16x16x32_bf16 v[44:47], v[152:155], v[204:207], v[44:47]
	v_mfma_f32_16x16x32_bf16 v[36:39], v[160:163], v[204:207], v[36:39]
	v_mfma_f32_16x16x32_bf16 v[28:31], v[152:155], v[212:215], v[28:31]
	v_mfma_f32_16x16x32_bf16 v[20:23], v[160:163], v[212:215], v[20:23]
	v_mfma_f32_16x16x32_bf16 v[12:15], v[152:155], v[226:229], v[12:15]
	v_mfma_f32_16x16x32_bf16 v[4:7], v[160:163], v[226:229], v[4:7]
	s_setprio 0
	s_setprio 1
	v_mfma_f32_16x16x32_bf16 v[56:59], v[164:167], v[180:183], v[56:59]
	v_mfma_f32_16x16x32_bf16 v[48:51], v[172:175], v[180:183], v[48:51]
	v_mfma_f32_16x16x32_bf16 v[40:43], v[164:167], v[200:203], v[40:43]
	v_mfma_f32_16x16x32_bf16 v[32:35], v[172:175], v[200:203], v[32:35]
	v_mfma_f32_16x16x32_bf16 v[24:27], v[164:167], v[208:211], v[24:27]
	v_mfma_f32_16x16x32_bf16 v[16:19], v[172:175], v[208:211], v[16:19]
	v_mfma_f32_16x16x32_bf16 v[8:11], v[164:167], v[216:219], v[8:11]
	v_mfma_f32_16x16x32_bf16 v[0:3], v[172:175], v[216:219], v[0:3]
	v_mfma_f32_16x16x32_bf16 v[56:59], v[168:171], v[184:187], v[56:59]
	v_mfma_f32_16x16x32_bf16 v[48:51], v[176:179], v[184:187], v[48:51]
	v_mfma_f32_16x16x32_bf16 v[40:43], v[168:171], v[204:207], v[40:43]
	v_mfma_f32_16x16x32_bf16 v[32:35], v[176:179], v[204:207], v[32:35]
	v_mfma_f32_16x16x32_bf16 v[24:27], v[168:171], v[212:215], v[24:27]
	v_mfma_f32_16x16x32_bf16 v[16:19], v[176:179], v[212:215], v[16:19]
	v_mfma_f32_16x16x32_bf16 v[8:11], v[168:171], v[226:229], v[8:11]
	v_mfma_f32_16x16x32_bf16 v[0:3], v[176:179], v[226:229], v[0:3]
	s_setprio 0
	s_barrier
	s_add_i32 s57, s57, 2
	s_add_u32 s55, s55, 0x100
	s_addc_u32 s56, s56, 0
	s_add_u32 s2, s2, 0x100
	s_addc_u32 s3, s3, 0
	s_cmp_gt_u32 s57, 13
	s_cbranch_scc0 .LBB0_1385
	s_and_b64 vcc, exec, s[10:11]
	s_cbranch_vccz .LBB0_1388
	s_barrier

; #define PG8_STAGE(bufoff, gbase, voff) do { _Pragma("unroll") for (int _i = 0; _i < 2; ++_i) \
;         __builtin_amdgcn_global_load_lds((const unsigned*)((const char*)(gbase) + (voff)[_i]), (PG8_LAS unsigned*)(lds + (bufoff) + ldsw + _i * 8192), 16, 0, 0); } while (0)
; #define PG8_LDA(dst, b, h) do { _Pragma("unroll") for (int m = 0; m < 4; ++m) _Pragma("unroll") for (int k = 0; k < 2; ++k) dst[m][k] = *(const PG8_LAS bf16x8*)(lds + PG8_SA(b, h) + aoff + m * 2048 + k * 1024); } while (0)
; #define PG8_LDB(dst, b, h) do { _Pragma("unroll") for (int n = 0; n < 2; ++n) _Pragma("unroll") for (int k = 0; k < 2; ++k) dst[n][k] = *(const PG8_LAS bf16x8*)(lds + PG8_SB(b, h) + boff + n * 2048 + k * 1024); } while (0)
; #define PG8_MMA(ai, bj, At, Bt) do { __builtin_amdgcn_s_setprio(1); _Pragma("unroll") for (int m = 0; m < 4; ++m) _Pragma("unroll") for (int n = 0; n < 2; ++n) _Pragma("unroll") for (int k = 0; k < 2; ++k) \
;         acc[ai][bj][m][n] = __builtin_amdgcn_mfma_f32_16x16x32_bf16(Bt[n][k], At[m][k], acc[ai][bj][m][n], 0, 0, 0); __builtin_amdgcn_s_setprio(0); } while (0)
; #define PG8_WAIT_V(n) asm volatile("s_waitcnt vmcnt(" #n ")" ::: "memory")
; #define PG8_WAIT_L(n) asm volatile("s_waitcnt lgkmcnt(" #n ")" ::: "memory")
; template <class Epi, class Sched, bool ALIGN_EPI = false, bool SP2 = false>
; __device__ __forceinline__ void gemm_phase(PG8_LAS unsigned char* lds, const Gemm g, const Sched& S, const Epi& E, int tid_in) {
;     ...
;             const bool last = (t == nt - 2);
;             const char* a1 = cA + (size_t)(t + 1) * kstep;
;             const char* a2 = last ? nA : cA + (size_t)(t + 2) * kstep; const char* b2 = last ? nB : cB + (size_t)(t + 2) * kstep;
;             const char* a3 = a2 + kstep; const char* b3 = b2 + kstep;
;             if (last && has_next) S.a_ready(nxt);
;             if constexpr (SP2) {
;             PG8_LDB(B0, 0, 0); PG8_LDB(B1, 0, 1); PG8_SCHED; PG8_LDA(At, 0, 0); PG8_STAGE(PG8_SA(1, 1), a1 + hstepA, voffA);
;             PG8_WAIT_V(8); PG8_WAIT_L(0); PG8_BAR; PG8_MMA(0, 0, At, B0); PG8_MMA(0, 1, At, B1); PG8_BAR; PG8_SCHED;
;             PG8_LDA(At, 0, 1); PG8_STAGE(PG8_SB(0, 0), b2, voffB); PG8_STAGE(PG8_SB(0, 1), b2 + hstep, voffB); PG8_STAGE(PG8_SA(0, 0), a2, voffA);
;             PG8_WAIT_V(8); PG8_WAIT_L(0); PG8_BAR; PG8_MMA(1, 0, At, B0); PG8_MMA(1, 1, At, B1); PG8_BAR; PG8_SCHED;
.LBB0_1479:
	s_add_u32 s14, s12, 0x100
	s_addc_u32 s15, s13, 0
	s_add_i32 s56, 0, 0x10000
	s_cmp_eq_u32 s55, 40
	s_cselect_b32 s25, s11, s15
	s_cselect_b32 s24, s10, s14
	s_cselect_b32 s21, s19, s45
	s_cselect_b32 s20, s18, s44
	s_add_i32 s57, 0, 0x14000
	v_add_u32_e32 v124, s56, v226
	v_add_u32_e32 v140, s57, v226
	ds_read_b128 v[112:115], v124
	ds_read_b128 v[116:119], v124 offset:1024
	ds_read_b128 v[120:123], v124 offset:2048
	ds_read_b128 v[124:127], v124 offset:3072
	ds_read_b128 v[128:131], v140
	ds_read_b128 v[132:135], v140 offset:1024
	ds_read_b128 v[136:139], v140 offset:2048
	ds_read_b128 v[140:143], v140 offset:3072
	s_add_i32 m0, s31, 0xc000
	ds_read_b128 v[144:147], v227
	ds_read_b128 v[148:151], v227 offset:1024
	ds_read_b128 v[152:155], v227 offset:2048
	ds_read_b128 v[156:159], v227 offset:3072
	ds_read_b128 v[176:179], v227 offset:4096
	ds_read_b128 v[180:183], v227 offset:5120
	ds_read_b128 v[208:211], v227 offset:6144
	global_load_lds_dwordx4 v206, s[12:13]
	s_add_i32 m0, s31, 0xe000
	ds_read_b128 v[212:215], v227 offset:7168
	global_load_lds_dwordx4 v204, s[12:13]
	s_waitcnt vmcnt(8)
	s_waitcnt lgkmcnt(0)
	s_barrier
	s_setprio 1
	v_mfma_f32_16x16x32_bf16 v[172:175], v[112:115], v[144:147], v[172:175]
	v_mfma_f32_16x16x32_bf16 v[168:171], v[120:123], v[144:147], v[168:171]
	v_mfma_f32_16x16x32_bf16 v[108:111], v[112:115], v[152:155], v[108:111]
	v_mfma_f32_16x16x32_bf16 v[104:107], v[120:123], v[152:155], v[104:107]
	v_mfma_f32_16x16x32_bf16 v[92:95], v[112:115], v[176:179], v[92:95]
	v_mfma_f32_16x16x32_bf16 v[88:91], v[120:123], v[176:179], v[88:91]
	v_mfma_f32_16x16x32_bf16 v[76:79], v[112:115], v[208:211], v[76:79]
	v_mfma_f32_16x16x32_bf16 v[72:75], v[120:123], v[208:211], v[72:75]
	v_mfma_f32_16x16x32_bf16 v[172:175], v[116:119], v[148:151], v[172:175]
	v_mfma_f32_16x16x32_bf16 v[168:171], v[124:127], v[148:151], v[168:171]
	v_mfma_f32_16x16x32_bf16 v[108:111], v[116:119], v[156:159], v[108:111]
	v_mfma_f32_16x16x32_bf16 v[104:107], v[124:127], v[156:159], v[104:107]
	v_mfma_f32_16x16x32_bf16 v[92:95], v[116:119], v[180:183], v[92:95]
	v_mfma_f32_16x16x32_bf16 v[88:91], v[124:127], v[180:183], v[88:91]
	v_mfma_f32_16x16x32_bf16 v[76:79], v[116:119], v[212:215], v[76:79]
	v_mfma_f32_16x16x32_bf16 v[72:75], v[124:127], v[212:215], v[72:75]
	s_setprio 0
	s_setprio 1
	v_mfma_f32_16x16x32_bf16 v[164:167], v[128:131], v[144:147], v[164:167]
	v_mfma_f32_16x16x32_bf16 v[100:103], v[128:131], v[152:155], v[100:103]
	v_mfma_f32_16x16x32_bf16 v[96:99], v[136:139], v[152:155], v[96:99]
	v_mfma_f32_16x16x32_bf16 v[84:87], v[128:131], v[176:179], v[84:87]
	v_mfma_f32_16x16x32_bf16 v[80:83], v[136:139], v[176:179], v[80:83]
	v_mfma_f32_16x16x32_bf16 v[68:71], v[128:131], v[208:211], v[68:71]
	v_mfma_f32_16x16x32_bf16 v[64:67], v[136:139], v[208:211], v[64:67]
	v_mfma_f32_16x16x32_bf16 v[164:167], v[132:135], v[148:151], v[164:167]
	v_mfma_f32_16x16x32_bf16 v[144:147], v[136:139], v[144:147], v[160:163]
	v_mfma_f32_16x16x32_bf16 v[100:103], v[132:135], v[156:159], v[100:103]
	v_mfma_f32_16x16x32_bf16 v[96:99], v[140:143], v[156:159], v[96:99]
	v_mfma_f32_16x16x32_bf16 v[84:87], v[132:135], v[180:183], v[84:87]
	v_mfma_f32_16x16x32_bf16 v[80:83], v[140:143], v[180:183], v[80:83]
	v_mfma_f32_16x16x32_bf16 v[68:71], v[132:135], v[212:215], v[68:71]
	v_mfma_f32_16x16x32_bf16 v[64:67], v[140:143], v[212:215], v[64:67]
	v_mfma_f32_16x16x32_bf16 v[144:147], v[140:143], v[148:151], v[144:147]
	s_setprio 0
	s_barrier
	s_add_i32 s12, s56, s30
	s_mov_b64 s[100:101], s[20:21]
	s_mov_b32 m0, s12
	ds_read_b128 v[148:151], v227 offset:16384
	ds_read_b128 v[152:155], v227 offset:17408
	ds_read_b128 v[156:159], v227 offset:18432
	ds_read_b128 v[160:163], v227 offset:19456
	ds_read_b128 v[176:179], v227 offset:20480
	ds_read_b128 v[180:183], v227 offset:21504
	global_load_lds_dwordx4 v190, s[100:101]
	s_add_i32 m0, s12, 0x2000
	s_add_u32 s12, s20, 0xb0000
	s_addc_u32 s13, s21, 0
	s_add_i32 s56, s57, s30
	global_load_lds_dwordx4 v184, s[100:101]
	s_mov_b32 m0, s56
	v_lshl_add_u64 v[232:233], s[24:25], 0, v[188:189]
	global_load_lds_dwordx4 v190, s[12:13]
	s_add_i32 m0, s56, 0x2000
	v_lshl_add_u64 v[234:235], s[24:25], 0, v[186:187]
	global_load_lds_dwordx4 v184, s[12:13]
	s_mov_b32 m0, s31
	ds_read_b128 v[208:211], v227 offset:22528
	global_load_lds_dwordx4 v[232:233], off
	s_mov_b32 m0, s34
	ds_read_b128 v[212:215], v227 offset:23552
	global_load_lds_dwordx4 v[234:235], off
	s_waitcnt vmcnt(8)
	s_waitcnt lgkmcnt(0)
	s_barrier
	s_setprio 1
	v_mfma_f32_16x16x32_bf16 v[60:63], v[112:115], v[148:151], v[60:63]
	v_mfma_f32_16x16x32_bf16 v[56:59], v[120:123], v[148:151], v[56:59]
	v_mfma_f32_16x16x32_bf16 v[44:47], v[112:115], v[156:159], v[44:47]
	v_mfma_f32_16x16x32_bf16 v[40:43], v[120:123], v[156:159], v[40:43]
	v_mfma_f32_16x16x32_bf16 v[28:31], v[112:115], v[176:179], v[28:31]
	v_mfma_f32_16x16x32_bf16 v[24:27], v[120:123], v[176:179], v[24:27]
	v_mfma_f32_16x16x32_bf16 v[12:15], v[112:115], v[208:211], v[12:15]
	v_mfma_f32_16x16x32_bf16 v[8:11], v[120:123], v[208:211], v[8:11]
	v_mfma_f32_16x16x32_bf16 v[60:63], v[116:119], v[152:155], v[60:63]
	v_mfma_f32_16x16x32_bf16 v[56:59], v[124:127], v[152:155], v[56:59]
	v_mfma_f32_16x16x32_bf16 v[44:47], v[116:119], v[160:163], v[44:47]
	v_mfma_f32_16x16x32_bf16 v[40:43], v[124:127], v[160:163], v[40:43]
	v_mfma_f32_16x16x32_bf16 v[28:31], v[116:119], v[180:183], v[28:31]
	v_mfma_f32_16x16x32_bf16 v[24:27], v[124:127], v[180:183], v[24:27]
	v_mfma_f32_16x16x32_bf16 v[12:15], v[116:119], v[212:215], v[12:15]
	v_mfma_f32_16x16x32_bf16 v[8:11], v[124:127], v[212:215], v[8:11]
	s_setprio 0
	s_setprio 1
	v_mfma_f32_16x16x32_bf16 v[52:55], v[128:131], v[148:151], v[52:55]
	v_mfma_f32_16x16x32_bf16 v[48:51], v[136:139], v[148:151], v[48:51]
	v_mfma_f32_16x16x32_bf16 v[36:39], v[128:131], v[156:159], v[36:39]
	v_mfma_f32_16x16x32_bf16 v[32:35], v[136:139], v[156:159], v[32:35]
	v_mfma_f32_16x16x32_bf16 v[20:23], v[128:131], v[176:179], v[20:23]
	v_mfma_f32_16x16x32_bf16 v[16:19], v[136:139], v[176:179], v[16:19]
	v_mfma_f32_16x16x32_bf16 v[4:7], v[128:131], v[208:211], v[4:7]
	v_mfma_f32_16x16x32_bf16 v[0:3], v[136:139], v[208:211], v[0:3]
	v_mfma_f32_16x16x32_bf16 v[52:55], v[132:135], v[152:155], v[52:55]
	v_mfma_f32_16x16x32_bf16 v[48:51], v[140:143], v[152:155], v[48:51]
	v_mfma_f32_16x16x32_bf16 v[36:39], v[132:135], v[160:163], v[36:39]
	v_mfma_f32_16x16x32_bf16 v[32:35], v[140:143], v[160:163], v[32:35]
	v_mfma_f32_16x16x32_bf16 v[20:23], v[132:135], v[180:183], v[20:23]
	v_mfma_f32_16x16x32_bf16 v[16:19], v[140:143], v[180:183], v[16:19]
	v_mfma_f32_16x16x32_bf16 v[4:7], v[132:135], v[212:215], v[4:7]
	v_mfma_f32_16x16x32_bf16 v[0:3], v[140:143], v[212:215], v[0:3]
	s_setprio 0
	s_barrier
; #define PG8_STAGE(bufoff, gbase, voff) do { _Pragma("unroll") for (int _i = 0; _i < 2; ++_i) \
;         __builtin_amdgcn_global_load_lds((const unsigned*)((const char*)(gbase) + (voff)[_i]), (PG8_LAS unsigned*)(lds + (bufoff) + ldsw + _i * 8192), 16, 0, 0); } while (0)
; #define PG8_LDA(dst, b, h) do { _Pragma("unroll") for (int m = 0; m < 4; ++m) _Pragma("unroll") for (int k = 0; k < 2; ++k) dst[m][k] = *(const PG8_LAS bf16x8*)(lds + PG8_SA(b, h) + aoff + m * 2048 + k * 1024); } while (0)
; #define PG8_LDB(dst, b, h) do { _Pragma("unroll") for (int n = 0; n < 2; ++n) _Pragma("unroll") for (int k = 0; k < 2; ++k) dst[n][k] = *(const PG8_LAS bf16x8*)(lds + PG8_SB(b, h) + boff + n * 2048 + k * 1024); } while (0)
; #define PG8_MMA(ai, bj, At, Bt) do { __builtin_amdgcn_s_setprio(1); _Pragma("unroll") for (int m = 0; m < 4; ++m) _Pragma("unroll") for (int n = 0; n < 2; ++n) _Pragma("unroll") for (int k = 0; k < 2; ++k) \
;         acc[ai][bj][m][n] = __builtin_amdgcn_mfma_f32_16x16x32_bf16(Bt[n][k], At[m][k], acc[ai][bj][m][n], 0, 0, 0); __builtin_amdgcn_s_setprio(0); } while (0)
; #define PG8_WAIT_V(n) asm volatile("s_waitcnt vmcnt(" #n ")" ::: "memory")
; #define PG8_WAIT_L(n) asm volatile("s_waitcnt lgkmcnt(" #n ")" ::: "memory")
; #define PG8_BAR __builtin_amdgcn_s_barrier()
; #define PG8_SCHED __builtin_amdgcn_sched_barrier(0)
; template <class Epi, class Sched, bool ALIGN_EPI = false, bool SP2 = false>
; __device__ __forceinline__ void gemm_phase(PG8_LAS unsigned char* lds, const Gemm g, const Sched& S, const Epi& E, int tid_in) {
;     ...
;             PG8_LDB(B0, 1, 0); PG8_LDB(B1, 1, 1); PG8_SCHED; PG8_LDA(At, 1, 0); PG8_STAGE(PG8_SA(0, 1), a2 + hstepA, voffA);
;             PG8_WAIT_V(8); PG8_WAIT_L(0); PG8_BAR; PG8_MMA(0, 0, At, B0); PG8_MMA(0, 1, At, B1); PG8_BAR; PG8_SCHED;
;             PG8_LDA(At, 1, 1); PG8_STAGE(PG8_SB(1, 0), b3, voffB); PG8_STAGE(PG8_SB(1, 1), b3 + hstep, voffB); PG8_STAGE(PG8_SA(1, 0), a3, voffA);
;             PG8_WAIT_V(8); PG8_WAIT_L(0); PG8_BAR; PG8_MMA(1, 0, At, B0); PG8_MMA(1, 1, At, B1); PG8_BAR; PG8_SCHED;
	s_add_i32 s56, 0, 0x18000
	s_add_i32 s57, 0, 0x1c000
	v_add_u32_e32 v124, s56, v226
	v_add_u32_e32 v140, s57, v226
	ds_read_b128 v[112:115], v124
	ds_read_b128 v[116:119], v124 offset:1024
	ds_read_b128 v[120:123], v124 offset:2048
	ds_read_b128 v[124:127], v124 offset:3072
	ds_read_b128 v[128:131], v140
	ds_read_b128 v[132:135], v140 offset:1024
	ds_read_b128 v[136:139], v140 offset:2048
	ds_read_b128 v[140:143], v140 offset:3072
	s_add_u32 s12, s24, 0xb0000
	s_addc_u32 s13, s25, 0
	s_mov_b32 m0, s35
	ds_read_b128 v[148:151], v227 offset:32768
	ds_read_b128 v[152:155], v227 offset:33792
	ds_read_b128 v[156:159], v227 offset:34816
	ds_read_b128 v[176:179], v227 offset:35840
	ds_read_b128 v[180:183], v227 offset:36864
	ds_read_b128 v[208:211], v227 offset:37888
	ds_read_b128 v[212:215], v227 offset:38912
	global_load_lds_dwordx4 v188, s[12:13]
	s_mov_b32 m0, s46
	ds_read_b128 v[216:219], v227 offset:39936
	global_load_lds_dwordx4 v186, s[12:13]
	s_waitcnt vmcnt(8)
	s_waitcnt lgkmcnt(0)
	s_barrier
	s_setprio 1
	v_mfma_f32_16x16x32_bf16 v[160:163], v[112:115], v[148:151], v[172:175]
	v_mfma_f32_16x16x32_bf16 v[172:175], v[116:119], v[152:155], v[160:163]
	v_mfma_f32_16x16x32_bf16 v[160:163], v[120:123], v[148:151], v[168:171]
	v_mfma_f32_16x16x32_bf16 v[108:111], v[112:115], v[156:159], v[108:111]
	v_mfma_f32_16x16x32_bf16 v[104:107], v[120:123], v[156:159], v[104:107]
	v_mfma_f32_16x16x32_bf16 v[92:95], v[112:115], v[180:183], v[92:95]
	v_mfma_f32_16x16x32_bf16 v[88:91], v[120:123], v[180:183], v[88:91]
	v_mfma_f32_16x16x32_bf16 v[76:79], v[112:115], v[212:215], v[76:79]
	v_mfma_f32_16x16x32_bf16 v[72:75], v[120:123], v[212:215], v[72:75]
	v_mfma_f32_16x16x32_bf16 v[168:171], v[124:127], v[152:155], v[160:163]
	v_mfma_f32_16x16x32_bf16 v[108:111], v[116:119], v[176:179], v[108:111]
	v_mfma_f32_16x16x32_bf16 v[104:107], v[124:127], v[176:179], v[104:107]
	v_mfma_f32_16x16x32_bf16 v[92:95], v[116:119], v[208:211], v[92:95]
	v_mfma_f32_16x16x32_bf16 v[88:91], v[124:127], v[208:211], v[88:91]
	v_mfma_f32_16x16x32_bf16 v[76:79], v[116:119], v[216:219], v[76:79]
	v_mfma_f32_16x16x32_bf16 v[72:75], v[124:127], v[216:219], v[72:75]
	s_setprio 0
	s_setprio 1
	v_mfma_f32_16x16x32_bf16 v[160:163], v[128:131], v[148:151], v[164:167]
	v_mfma_f32_16x16x32_bf16 v[144:147], v[136:139], v[148:151], v[144:147]
	v_mfma_f32_16x16x32_bf16 v[100:103], v[128:131], v[156:159], v[100:103]
	v_mfma_f32_16x16x32_bf16 v[96:99], v[136:139], v[156:159], v[96:99]
	v_mfma_f32_16x16x32_bf16 v[84:87], v[128:131], v[180:183], v[84:87]
	v_mfma_f32_16x16x32_bf16 v[80:83], v[136:139], v[180:183], v[80:83]
	v_mfma_f32_16x16x32_bf16 v[68:71], v[128:131], v[212:215], v[68:71]
	v_mfma_f32_16x16x32_bf16 v[64:67], v[136:139], v[212:215], v[64:67]
	v_mfma_f32_16x16x32_bf16 v[164:167], v[132:135], v[152:155], v[160:163]
	v_mfma_f32_16x16x32_bf16 v[160:163], v[140:143], v[152:155], v[144:147]
	v_mfma_f32_16x16x32_bf16 v[100:103], v[132:135], v[176:179], v[100:103]
	v_mfma_f32_16x16x32_bf16 v[96:99], v[140:143], v[176:179], v[96:99]
	v_mfma_f32_16x16x32_bf16 v[84:87], v[132:135], v[208:211], v[84:87]
	v_mfma_f32_16x16x32_bf16 v[80:83], v[140:143], v[208:211], v[80:83]
	v_mfma_f32_16x16x32_bf16 v[68:71], v[132:135], v[216:219], v[68:71]
	v_mfma_f32_16x16x32_bf16 v[64:67], v[140:143], v[216:219], v[64:67]
	s_setprio 0
	s_barrier
	s_add_i32 s12, s56, s30
	s_mov_b32 m0, s12
	ds_read_b128 v[144:147], v227 offset:49152
	ds_read_b128 v[148:151], v227 offset:50176
	ds_read_b128 v[152:155], v227 offset:51200
	ds_read_b128 v[156:159], v227 offset:52224
	s_add_u32 s100, s100, 0x80
	s_addc_u32 s101, s101, 0
	global_load_lds_dwordx4 v190, s[100:101]
	s_add_i32 m0, s12, 0x2000
	s_add_u32 s12, s20, 0xb0080
	s_addc_u32 s13, s21, 0
	s_add_i32 s20, s57, s30
	global_load_lds_dwordx4 v184, s[100:101]
	s_mov_b32 m0, s20
	ds_read_b128 v[176:179], v227 offset:53248
	global_load_lds_dwordx4 v190, s[12:13]
	s_add_i32 m0, s20, 0x2000
	ds_read_b128 v[180:183], v227 offset:54272
	global_load_lds_dwordx4 v184, s[12:13]
	v_lshl_add_u64 v[216:217], v[232:233], 0, s[0:1]
	s_mov_b32 m0, s49
	ds_read_b128 v[208:211], v227 offset:55296
	global_load_lds_dwordx4 v[216:217], off
	v_lshl_add_u64 v[216:217], v[234:235], 0, s[0:1]
	s_mov_b32 m0, s50
	ds_read_b128 v[212:215], v227 offset:56320
	global_load_lds_dwordx4 v[216:217], off
	s_waitcnt vmcnt(8)
	s_waitcnt lgkmcnt(0)
	s_barrier
	s_setprio 1
	v_mfma_f32_16x16x32_bf16 v[60:63], v[112:115], v[144:147], v[60:63]
	v_mfma_f32_16x16x32_bf16 v[56:59], v[120:123], v[144:147], v[56:59]
	v_mfma_f32_16x16x32_bf16 v[44:47], v[112:115], v[152:155], v[44:47]
	v_mfma_f32_16x16x32_bf16 v[40:43], v[120:123], v[152:155], v[40:43]
	v_mfma_f32_16x16x32_bf16 v[28:31], v[112:115], v[176:179], v[28:31]
	v_mfma_f32_16x16x32_bf16 v[24:27], v[120:123], v[176:179], v[24:27]
	v_mfma_f32_16x16x32_bf16 v[12:15], v[112:115], v[208:211], v[12:15]
	v_mfma_f32_16x16x32_bf16 v[8:11], v[120:123], v[208:211], v[8:11]
	v_mfma_f32_16x16x32_bf16 v[60:63], v[116:119], v[148:151], v[60:63]
	v_mfma_f32_16x16x32_bf16 v[56:59], v[124:127], v[148:151], v[56:59]
	v_mfma_f32_16x16x32_bf16 v[44:47], v[116:119], v[156:159], v[44:47]
	v_mfma_f32_16x16x32_bf16 v[40:43], v[124:127], v[156:159], v[40:43]
	v_mfma_f32_16x16x32_bf16 v[28:31], v[116:119], v[180:183], v[28:31]
	v_mfma_f32_16x16x32_bf16 v[24:27], v[124:127], v[180:183], v[24:27]
	v_mfma_f32_16x16x32_bf16 v[12:15], v[116:119], v[212:215], v[12:15]
	v_mfma_f32_16x16x32_bf16 v[8:11], v[124:127], v[212:215], v[8:11]
	s_setprio 0
	s_setprio 1
	v_mfma_f32_16x16x32_bf16 v[52:55], v[128:131], v[144:147], v[52:55]
	v_mfma_f32_16x16x32_bf16 v[48:51], v[136:139], v[144:147], v[48:51]
	v_mfma_f32_16x16x32_bf16 v[36:39], v[128:131], v[152:155], v[36:39]
	v_mfma_f32_16x16x32_bf16 v[32:35], v[136:139], v[152:155], v[32:35]
	v_mfma_f32_16x16x32_bf16 v[20:23], v[128:131], v[176:179], v[20:23]
	v_mfma_f32_16x16x32_bf16 v[16:19], v[136:139], v[176:179], v[16:19]
	v_mfma_f32_16x16x32_bf16 v[4:7], v[128:131], v[208:211], v[4:7]
	v_mfma_f32_16x16x32_bf16 v[0:3], v[136:139], v[208:211], v[0:3]
	v_mfma_f32_16x16x32_bf16 v[52:55], v[132:135], v[148:151], v[52:55]
	v_mfma_f32_16x16x32_bf16 v[48:51], v[140:143], v[148:151], v[48:51]
	v_mfma_f32_16x16x32_bf16 v[36:39], v[132:135], v[156:159], v[36:39]
	v_mfma_f32_16x16x32_bf16 v[32:35], v[140:143], v[156:159], v[32:35]
	v_mfma_f32_16x16x32_bf16 v[20:23], v[132:135], v[180:183], v[20:23]
	v_mfma_f32_16x16x32_bf16 v[16:19], v[140:143], v[180:183], v[16:19]
	v_mfma_f32_16x16x32_bf16 v[4:7], v[132:135], v[212:215], v[4:7]
	v_mfma_f32_16x16x32_bf16 v[0:3], v[140:143], v[212:215], v[0:3]
	s_setprio 0
	s_barrier
	s_add_i32 s55, s55, 2
	s_add_u32 s44, s44, 0x100
	s_addc_u32 s45, s45, 0
	s_cmp_gt_u32 s55, 41
	s_mov_b64 s[12:13], s[14:15]
	s_cbranch_scc0 .LBB0_1479
	s_and_b64 vcc, exec, s[8:9]
	s_cbranch_vccz .LBB0_1482
	s_barrier
